# attention: masked (previous/next block) chunks as per-wave static pair lists, software-pipelined; diagonal masks computed on the fly
# baseline (speedup 1.0000x reference)
; __device__ __forceinline__ unsigned cvtpk(float lo, float hi) { f32x2_t v = {lo, hi}; bf16x2_t b = __builtin_convertvector(v, bf16x2_t); return __builtin_bit_cast(unsigned, b); }
; __device__ __forceinline__ bool attn_unit(const Ptrs& P, LAS unsigned char* lds, int unit, int tid, int wave, int lane, bool pre, int nxt) {
;     ...
;         for (int kt = 0; kt < 4; ++kt) {
;             if (c == 0 && 32 * kt + 31 < q0) continue;
;             if (c == 2 && 32 * kt > q0 + 63) continue;
;             bf16x8_t kf[4], vf[2][2];
; #pragma unroll
;             for (int ds = 0; ds < 4; ++ds) kf[ds] = *(const LAS bf16x8_t*)(Kl + (32 * kt + r) * AT_KP + (16 * ds + 8 * hh) * 2);
; #pragma unroll
;             for (int db = 0; db < 2; ++db)
; #pragma unroll
;                 for (int s = 0; s < 2; ++s) vf[db][s] = *(const LAS bf16x8_t*)(Vl + (32 * db + r) * AT_VP + (32 * kt + 16 * s + 8 * hh) * 2);
; #pragma unroll
;             for (int cb = 0; cb < 2; ++cb) {
;                 const int dq = 32 * kt - (q0 + 32 * cb);
;                 if ((c == 0 && dq < 0) || (c == 2 && dq > 0)) continue;
;                 const bool diag = (c == 0 || c == 2) && dq == 0;
;                 f32x16 st = MFMA32(kf[0], qf[cb][0], negm);
;                 st = MFMA32(kf[1], qf[cb][1], st); st = MFMA32(kf[2], qf[cb][2], st); st = MFMA32(kf[3], qf[cb][3], st);
;                 float p[16];
; #pragma unroll
;                 for (int i = 0; i < 16; ++i) p[i] = __builtin_amdgcn_exp2f(st[i]);
;                 if (diag) {
;                     const int thr = r - 4 * hh;
; #pragma unroll
;                     for (int i = 0; i < 16; ++i) { const bool vis = c == 0 ? crow(i, 0) >= thr : crow(i, 0) <= thr; p[i] = vis ? p[i] : 0.f; }
;                 }
;                 float s4 = 0.f;
; #pragma unroll
;                 for (int i = 0; i < 16; ++i) s4 += p[i];
;                 rs[cb] += s4;
; #pragma unroll
;                 for (int s = 0; s < 2; ++s) {
;                     u32x4 w; w.x = cvtpk(p[8 * s], p[8 * s + 1]); w.y = cvtpk(p[8 * s + 2], p[8 * s + 3]); w.z = cvtpk(p[8 * s + 4], p[8 * s + 5]); w.w = cvtpk(p[8 * s + 6], p[8 * s + 7]);
;                     const bf16x8_t pb = __builtin_bit_cast(bf16x8_t, w);
;                     o[0][cb] = MFMA32(vf[0][s], pb, o[0][cb]); o[1][cb] = MFMA32(vf[1][s], pb, o[1][cb]);
;                 }
;             }
;         }
.LBB9_341:
	v_and_b32_e32 v162, 31, v170
	v_lshrrev_b32_e32 v163, 5, v170
	v_lshlrev_b32_e32 v163, 2, v163
	v_sub_u32_e32 v162, v162, v163
	s_cmp_eq_u32 s33, 0
	s_cbranch_scc0 .Lam0_hi
	ds_read_b128 v[238:241], v196 offset:0
	ds_read_b128 v[242:245], v196 offset:32
	ds_read_b128 v[246:249], v196 offset:64
	ds_read_b128 v[204:207], v196 offset:96
	s_waitcnt lgkmcnt(0)
	v_mfma_f32_32x32x16_bf16 v[82:97], v[238:241], v[114:117], v[18:33]
	v_mfma_f32_32x32x16_bf16 v[82:97], v[242:245], v[118:121], v[82:97]
	v_mfma_f32_32x32x16_bf16 v[82:97], v[246:249], v[122:125], v[82:97]
	v_mfma_f32_32x32x16_bf16 v[82:97], v[204:207], v[126:129], v[82:97]
	ds_read_b128 v[238:241], v196 offset:4608
	ds_read_b128 v[242:245], v196 offset:4640
	ds_read_b128 v[246:249], v196 offset:4672
	ds_read_b128 v[204:207], v196 offset:4704
	s_waitcnt lgkmcnt(0)
	v_mfma_f32_32x32x16_bf16 v[98:113], v[238:241], v[114:117], v[18:33]
	v_mfma_f32_32x32x16_bf16 v[98:113], v[242:245], v[118:121], v[98:113]
	v_mfma_f32_32x32x16_bf16 v[98:113], v[246:249], v[122:125], v[98:113]
	v_mfma_f32_32x32x16_bf16 v[98:113], v[204:207], v[126:129], v[98:113]
	ds_read_b128 v[146:149], v195 offset:0
	ds_read_b128 v[150:153], v195 offset:32
	ds_read_b128 v[154:157], v194 offset:0
	ds_read_b128 v[158:161], v194 offset:32
	s_nop 3
	v_exp_f32_e32 v82, v82
	v_exp_f32_e32 v83, v83
	v_exp_f32_e32 v84, v84
	v_exp_f32_e32 v85, v85
	v_exp_f32_e32 v86, v86
	v_exp_f32_e32 v87, v87
	v_exp_f32_e32 v88, v88
	v_exp_f32_e32 v89, v89
	v_exp_f32_e32 v90, v90
	v_exp_f32_e32 v91, v91
	v_exp_f32_e32 v92, v92
	v_exp_f32_e32 v93, v93
	v_exp_f32_e32 v94, v94
	v_exp_f32_e32 v95, v95
	v_exp_f32_e32 v96, v96
	v_exp_f32_e32 v97, v97
	v_cmp_ge_i32_e32 vcc, 0, v162
	v_cmp_ge_i32_e64 s[98:99], 1, v162
	s_nop 0
	v_cndmask_b32_e32 v82, 0, v82, vcc
	v_cmp_ge_i32_e32 vcc, 2, v162
	v_cndmask_b32_e64 v83, 0, v83, s[98:99]
	v_cmp_ge_i32_e64 s[98:99], 3, v162
	v_cndmask_b32_e32 v84, 0, v84, vcc
	v_cmp_ge_i32_e32 vcc, 8, v162
	v_cndmask_b32_e64 v85, 0, v85, s[98:99]
	v_cmp_ge_i32_e64 s[98:99], 9, v162
	v_cndmask_b32_e32 v86, 0, v86, vcc
	v_cmp_ge_i32_e32 vcc, 10, v162
	v_cndmask_b32_e64 v87, 0, v87, s[98:99]
	v_cmp_ge_i32_e64 s[98:99], 11, v162
	v_cndmask_b32_e32 v88, 0, v88, vcc
	v_cmp_ge_i32_e32 vcc, 16, v162
	v_cndmask_b32_e64 v89, 0, v89, s[98:99]
	v_cmp_ge_i32_e64 s[98:99], 17, v162
	v_cndmask_b32_e32 v90, 0, v90, vcc
	v_cmp_ge_i32_e32 vcc, 18, v162
	v_cndmask_b32_e64 v91, 0, v91, s[98:99]
	v_cmp_ge_i32_e64 s[98:99], 19, v162
	v_cndmask_b32_e32 v92, 0, v92, vcc
	v_cmp_ge_i32_e32 vcc, 24, v162
	v_cndmask_b32_e64 v93, 0, v93, s[98:99]
	v_cmp_ge_i32_e64 s[98:99], 25, v162
	v_cndmask_b32_e32 v94, 0, v94, vcc
	v_cmp_ge_i32_e32 vcc, 26, v162
	v_cndmask_b32_e64 v95, 0, v95, s[98:99]
	v_cmp_ge_i32_e64 s[98:99], 27, v162
	v_cndmask_b32_e32 v96, 0, v96, vcc
	s_nop 0
	v_cndmask_b32_e64 v97, 0, v97, s[98:99]
	s_nop 0
	v_add_f32_e32 v183, v82, v183
	v_add_f32_e32 v183, v83, v183
	v_add_f32_e32 v183, v84, v183
	v_add_f32_e32 v183, v85, v183
	v_add_f32_e32 v183, v86, v183
	v_add_f32_e32 v183, v87, v183
	v_add_f32_e32 v183, v88, v183
	v_add_f32_e32 v183, v89, v183
	v_add_f32_e32 v183, v90, v183
	v_add_f32_e32 v183, v91, v183
	v_add_f32_e32 v183, v92, v183
	v_add_f32_e32 v183, v93, v183
	v_add_f32_e32 v183, v94, v183
	v_add_f32_e32 v183, v95, v183
	v_add_f32_e32 v183, v96, v183
	v_add_f32_e32 v183, v97, v183
	v_cvt_pk_bf16_f32 v82, v82, v83
	v_cvt_pk_bf16_f32 v83, v84, v85
	v_cvt_pk_bf16_f32 v84, v86, v87
	v_cvt_pk_bf16_f32 v85, v88, v89
	v_cvt_pk_bf16_f32 v86, v90, v91
	v_cvt_pk_bf16_f32 v87, v92, v93
	v_cvt_pk_bf16_f32 v88, v94, v95
	v_cvt_pk_bf16_f32 v89, v96, v97
	s_nop 0
	s_waitcnt lgkmcnt(0)
	v_mfma_f32_32x32x16_bf16 v[66:81], v[146:149], v[82:85], v[66:81]
	v_mfma_f32_32x32x16_bf16 v[50:65], v[154:157], v[82:85], v[50:65]
	v_exp_f32_e32 v98, v98
	v_exp_f32_e32 v99, v99
	v_exp_f32_e32 v100, v100
	v_exp_f32_e32 v101, v101
	v_exp_f32_e32 v102, v102
	v_mfma_f32_32x32x16_bf16 v[66:81], v[150:153], v[86:89], v[66:81]
	v_exp_f32_e32 v103, v103
	v_exp_f32_e32 v104, v104
	v_exp_f32_e32 v105, v105
	v_exp_f32_e32 v106, v106
	v_exp_f32_e32 v107, v107
	v_mfma_f32_32x32x16_bf16 v[50:65], v[158:161], v[86:89], v[50:65]
	ds_read_b128 v[146:149], v195 offset:64
	ds_read_b128 v[150:153], v195 offset:96
	ds_read_b128 v[154:157], v194 offset:64
	ds_read_b128 v[158:161], v194 offset:96
	v_exp_f32_e32 v108, v108
	v_exp_f32_e32 v109, v109
	v_exp_f32_e32 v110, v110
	v_exp_f32_e32 v111, v111
	v_exp_f32_e32 v112, v112
	s_waitcnt lgkmcnt(0)
	v_mfma_f32_32x32x16_bf16 v[82:97], v[238:241], v[130:133], v[18:33]
	v_exp_f32_e32 v113, v113
	v_add_f32_e32 v183, v98, v183
	v_add_f32_e32 v183, v99, v183
	v_add_f32_e32 v183, v100, v183
	v_add_f32_e32 v183, v101, v183
	v_mfma_f32_32x32x16_bf16 v[82:97], v[242:245], v[134:137], v[82:97]
	v_add_f32_e32 v183, v102, v183
	v_add_f32_e32 v183, v103, v183
	v_add_f32_e32 v183, v104, v183
	v_add_f32_e32 v183, v105, v183
	v_add_f32_e32 v183, v106, v183
	v_mfma_f32_32x32x16_bf16 v[82:97], v[246:249], v[138:141], v[82:97]
	v_add_f32_e32 v183, v107, v183
	v_add_f32_e32 v183, v108, v183
	v_add_f32_e32 v183, v109, v183
	v_add_f32_e32 v183, v110, v183
	v_add_f32_e32 v183, v111, v183
	v_mfma_f32_32x32x16_bf16 v[82:97], v[204:207], v[142:145], v[82:97]
	ds_read_b128 v[238:241], v196 offset:9216
	ds_read_b128 v[242:245], v196 offset:9248
	ds_read_b128 v[246:249], v196 offset:9280
	ds_read_b128 v[204:207], v196 offset:9312
	v_add_f32_e32 v183, v112, v183
	v_add_f32_e32 v183, v113, v183
	v_cvt_pk_bf16_f32 v98, v98, v99
	v_cvt_pk_bf16_f32 v99, v100, v101
	v_cvt_pk_bf16_f32 v100, v102, v103
	v_cvt_pk_bf16_f32 v101, v104, v105
	v_cvt_pk_bf16_f32 v102, v106, v107
	v_cvt_pk_bf16_f32 v103, v108, v109
	v_cvt_pk_bf16_f32 v104, v110, v111
	v_cvt_pk_bf16_f32 v105, v112, v113
	s_nop 0
	s_waitcnt lgkmcnt(0)
; __device__ __forceinline__ unsigned cvtpk(float lo, float hi) { f32x2_t v = {lo, hi}; bf16x2_t b = __builtin_convertvector(v, bf16x2_t); return __builtin_bit_cast(unsigned, b); }
; __device__ __forceinline__ bool attn_unit(const Ptrs& P, LAS unsigned char* lds, int unit, int tid, int wave, int lane, bool pre, int nxt) {
;     ...
;         for (int kt = 0; kt < 4; ++kt) {
;             if (c == 0 && 32 * kt + 31 < q0) continue;
;             if (c == 2 && 32 * kt > q0 + 63) continue;
;             bf16x8_t kf[4], vf[2][2];
; #pragma unroll
;             for (int ds = 0; ds < 4; ++ds) kf[ds] = *(const LAS bf16x8_t*)(Kl + (32 * kt + r) * AT_KP + (16 * ds + 8 * hh) * 2);
; #pragma unroll
;             for (int db = 0; db < 2; ++db)
; #pragma unroll
;                 for (int s = 0; s < 2; ++s) vf[db][s] = *(const LAS bf16x8_t*)(Vl + (32 * db + r) * AT_VP + (32 * kt + 16 * s + 8 * hh) * 2);
; #pragma unroll
;             for (int cb = 0; cb < 2; ++cb) {
;                 const int dq = 32 * kt - (q0 + 32 * cb);
;                 if ((c == 0 && dq < 0) || (c == 2 && dq > 0)) continue;
;                 const bool diag = (c == 0 || c == 2) && dq == 0;
;                 f32x16 st = MFMA32(kf[0], qf[cb][0], negm);
;                 st = MFMA32(kf[1], qf[cb][1], st); st = MFMA32(kf[2], qf[cb][2], st); st = MFMA32(kf[3], qf[cb][3], st);
;                 float p[16];
; #pragma unroll
;                 for (int i = 0; i < 16; ++i) p[i] = __builtin_amdgcn_exp2f(st[i]);
;                 if (diag) {
;                     const int thr = r - 4 * hh;
; #pragma unroll
;                     for (int i = 0; i < 16; ++i) { const bool vis = c == 0 ? crow(i, 0) >= thr : crow(i, 0) <= thr; p[i] = vis ? p[i] : 0.f; }
;                 }
;                 float s4 = 0.f;
; #pragma unroll
;                 for (int i = 0; i < 16; ++i) s4 += p[i];
;                 rs[cb] += s4;
; #pragma unroll
;                 for (int s = 0; s < 2; ++s) {
;                     u32x4 w; w.x = cvtpk(p[8 * s], p[8 * s + 1]); w.y = cvtpk(p[8 * s + 2], p[8 * s + 3]); w.z = cvtpk(p[8 * s + 4], p[8 * s + 5]); w.w = cvtpk(p[8 * s + 6], p[8 * s + 7]);
;                     const bf16x8_t pb = __builtin_bit_cast(bf16x8_t, w);
;                     o[0][cb] = MFMA32(vf[0][s], pb, o[0][cb]); o[1][cb] = MFMA32(vf[1][s], pb, o[1][cb]);
;                 }
;             }
;         }
	v_mfma_f32_32x32x16_bf16 v[66:81], v[146:149], v[98:101], v[66:81]
	v_mfma_f32_32x32x16_bf16 v[50:65], v[154:157], v[98:101], v[50:65]
	v_exp_f32_e32 v82, v82
	v_exp_f32_e32 v83, v83
	v_exp_f32_e32 v84, v84
	v_exp_f32_e32 v85, v85
	v_exp_f32_e32 v86, v86
	v_mfma_f32_32x32x16_bf16 v[66:81], v[150:153], v[102:105], v[66:81]
	v_exp_f32_e32 v87, v87
	v_exp_f32_e32 v88, v88
	v_exp_f32_e32 v89, v89
	v_exp_f32_e32 v90, v90
	v_exp_f32_e32 v91, v91
	v_mfma_f32_32x32x16_bf16 v[50:65], v[158:161], v[102:105], v[50:65]
	v_exp_f32_e32 v92, v92
	v_exp_f32_e32 v93, v93
	v_exp_f32_e32 v94, v94
	v_exp_f32_e32 v95, v95
	v_exp_f32_e32 v96, v96
	s_waitcnt lgkmcnt(0)
	v_mfma_f32_32x32x16_bf16 v[98:113], v[238:241], v[114:117], v[18:33]
	v_exp_f32_e32 v97, v97
	v_cmp_ge_i32_e32 vcc, 0, v162
	v_cmp_ge_i32_e64 s[98:99], 1, v162
	s_nop 0
	v_cndmask_b32_e32 v82, 0, v82, vcc
	v_mfma_f32_32x32x16_bf16 v[98:113], v[242:245], v[118:121], v[98:113]
	v_cmp_ge_i32_e32 vcc, 2, v162
	v_cndmask_b32_e64 v83, 0, v83, s[98:99]
	v_cmp_ge_i32_e64 s[98:99], 3, v162
	v_cndmask_b32_e32 v84, 0, v84, vcc
	v_cmp_ge_i32_e32 vcc, 8, v162
	v_mfma_f32_32x32x16_bf16 v[98:113], v[246:249], v[122:125], v[98:113]
	v_cndmask_b32_e64 v85, 0, v85, s[98:99]
	v_cmp_ge_i32_e64 s[98:99], 9, v162
	v_cndmask_b32_e32 v86, 0, v86, vcc
	v_cmp_ge_i32_e32 vcc, 10, v162
	v_cndmask_b32_e64 v87, 0, v87, s[98:99]
	v_mfma_f32_32x32x16_bf16 v[98:113], v[204:207], v[126:129], v[98:113]
	v_cmp_ge_i32_e64 s[98:99], 11, v162
	v_cndmask_b32_e32 v88, 0, v88, vcc
	v_cmp_ge_i32_e32 vcc, 16, v162
	v_cndmask_b32_e64 v89, 0, v89, s[98:99]
	v_cmp_ge_i32_e64 s[98:99], 17, v162
	v_cndmask_b32_e32 v90, 0, v90, vcc
	v_cmp_ge_i32_e32 vcc, 18, v162
	v_cndmask_b32_e64 v91, 0, v91, s[98:99]
	v_cmp_ge_i32_e64 s[98:99], 19, v162
	v_cndmask_b32_e32 v92, 0, v92, vcc
	v_cmp_ge_i32_e32 vcc, 24, v162
	v_cndmask_b32_e64 v93, 0, v93, s[98:99]
	v_cmp_ge_i32_e64 s[98:99], 25, v162
	v_cndmask_b32_e32 v94, 0, v94, vcc
	v_cmp_ge_i32_e32 vcc, 26, v162
	v_cndmask_b32_e64 v95, 0, v95, s[98:99]
	v_cmp_ge_i32_e64 s[98:99], 27, v162
	v_cndmask_b32_e32 v96, 0, v96, vcc
	s_nop 0
	v_cndmask_b32_e64 v97, 0, v97, s[98:99]
	s_nop 0
	v_add_f32_e32 v182, v82, v182
	v_add_f32_e32 v182, v83, v182
	v_add_f32_e32 v182, v84, v182
	v_add_f32_e32 v182, v85, v182
	v_add_f32_e32 v182, v86, v182
	v_add_f32_e32 v182, v87, v182
	v_add_f32_e32 v182, v88, v182
	v_add_f32_e32 v182, v89, v182
	v_add_f32_e32 v182, v90, v182
	v_add_f32_e32 v182, v91, v182
	v_add_f32_e32 v182, v92, v182
	v_add_f32_e32 v182, v93, v182
	v_add_f32_e32 v182, v94, v182
	v_add_f32_e32 v182, v95, v182
	v_add_f32_e32 v182, v96, v182
	v_add_f32_e32 v182, v97, v182
	v_cvt_pk_bf16_f32 v82, v82, v83
	v_cvt_pk_bf16_f32 v83, v84, v85
	v_cvt_pk_bf16_f32 v84, v86, v87
	v_cvt_pk_bf16_f32 v85, v88, v89
	v_cvt_pk_bf16_f32 v86, v90, v91
	v_cvt_pk_bf16_f32 v87, v92, v93
	v_cvt_pk_bf16_f32 v88, v94, v95
	v_cvt_pk_bf16_f32 v89, v96, v97
	s_nop 0
	s_waitcnt lgkmcnt(0)
	v_mfma_f32_32x32x16_bf16 v[34:49], v[146:149], v[82:85], v[34:49]
	v_mfma_f32_32x32x16_bf16 v[2:17], v[154:157], v[82:85], v[2:17]
	v_exp_f32_e32 v98, v98
	v_exp_f32_e32 v99, v99
	v_exp_f32_e32 v100, v100
	v_exp_f32_e32 v101, v101
	v_exp_f32_e32 v102, v102
	v_mfma_f32_32x32x16_bf16 v[34:49], v[150:153], v[86:89], v[34:49]
	v_exp_f32_e32 v103, v103
	v_exp_f32_e32 v104, v104
	v_exp_f32_e32 v105, v105
	v_exp_f32_e32 v106, v106
	v_exp_f32_e32 v107, v107
	v_mfma_f32_32x32x16_bf16 v[2:17], v[158:161], v[86:89], v[2:17]
	ds_read_b128 v[146:149], v195 offset:128
	ds_read_b128 v[150:153], v195 offset:160
	ds_read_b128 v[154:157], v194 offset:128
	ds_read_b128 v[158:161], v194 offset:160
	v_exp_f32_e32 v108, v108
	v_exp_f32_e32 v109, v109
	v_exp_f32_e32 v110, v110
	v_exp_f32_e32 v111, v111
	v_exp_f32_e32 v112, v112
	s_waitcnt lgkmcnt(0)
	v_mfma_f32_32x32x16_bf16 v[82:97], v[238:241], v[130:133], v[18:33]
	v_exp_f32_e32 v113, v113
	v_add_f32_e32 v183, v98, v183
	v_add_f32_e32 v183, v99, v183
	v_add_f32_e32 v183, v100, v183
	v_add_f32_e32 v183, v101, v183
	v_mfma_f32_32x32x16_bf16 v[82:97], v[242:245], v[134:137], v[82:97]
	v_add_f32_e32 v183, v102, v183
	v_add_f32_e32 v183, v103, v183
	v_add_f32_e32 v183, v104, v183
	v_add_f32_e32 v183, v105, v183
	v_add_f32_e32 v183, v106, v183
	v_mfma_f32_32x32x16_bf16 v[82:97], v[246:249], v[138:141], v[82:97]
	v_add_f32_e32 v183, v107, v183
	v_add_f32_e32 v183, v108, v183
	v_add_f32_e32 v183, v109, v183
	v_add_f32_e32 v183, v110, v183
	v_add_f32_e32 v183, v111, v183
	v_mfma_f32_32x32x16_bf16 v[82:97], v[204:207], v[142:145], v[82:97]
	ds_read_b128 v[238:241], v196 offset:13824
	ds_read_b128 v[242:245], v196 offset:13856
	ds_read_b128 v[246:249], v196 offset:13888
	ds_read_b128 v[204:207], v196 offset:13920
	v_add_f32_e32 v183, v112, v183
	v_add_f32_e32 v183, v113, v183
	v_cvt_pk_bf16_f32 v98, v98, v99
	v_cvt_pk_bf16_f32 v99, v100, v101
	v_cvt_pk_bf16_f32 v100, v102, v103
	v_cvt_pk_bf16_f32 v101, v104, v105
	v_cvt_pk_bf16_f32 v102, v106, v107
	v_cvt_pk_bf16_f32 v103, v108, v109
	v_cvt_pk_bf16_f32 v104, v110, v111
	v_cvt_pk_bf16_f32 v105, v112, v113
	s_nop 0
	s_waitcnt lgkmcnt(0)
	v_mfma_f32_32x32x16_bf16 v[66:81], v[146:149], v[98:101], v[66:81]
	v_mfma_f32_32x32x16_bf16 v[50:65], v[154:157], v[98:101], v[50:65]
	v_exp_f32_e32 v82, v82
	v_exp_f32_e32 v83, v83
	v_exp_f32_e32 v84, v84
	v_exp_f32_e32 v85, v85
	v_exp_f32_e32 v86, v86
	v_mfma_f32_32x32x16_bf16 v[66:81], v[150:153], v[102:105], v[66:81]
	v_exp_f32_e32 v87, v87
	v_exp_f32_e32 v88, v88
	v_exp_f32_e32 v89, v89
	v_exp_f32_e32 v90, v90
	v_exp_f32_e32 v91, v91
	v_mfma_f32_32x32x16_bf16 v[50:65], v[158:161], v[102:105], v[50:65]
	v_exp_f32_e32 v92, v92
	v_exp_f32_e32 v93, v93
	v_exp_f32_e32 v94, v94
	v_exp_f32_e32 v95, v95
	v_exp_f32_e32 v96, v96
	s_waitcnt lgkmcnt(0)
; __device__ __forceinline__ unsigned cvtpk(float lo, float hi) { f32x2_t v = {lo, hi}; bf16x2_t b = __builtin_convertvector(v, bf16x2_t); return __builtin_bit_cast(unsigned, b); }
; __device__ __forceinline__ bool attn_unit(const Ptrs& P, LAS unsigned char* lds, int unit, int tid, int wave, int lane, bool pre, int nxt) {
;     ...
;         for (int kt = 0; kt < 4; ++kt) {
;             if (c == 0 && 32 * kt + 31 < q0) continue;
;             if (c == 2 && 32 * kt > q0 + 63) continue;
;             bf16x8_t kf[4], vf[2][2];
; #pragma unroll
;             for (int ds = 0; ds < 4; ++ds) kf[ds] = *(const LAS bf16x8_t*)(Kl + (32 * kt + r) * AT_KP + (16 * ds + 8 * hh) * 2);
; #pragma unroll
;             for (int db = 0; db < 2; ++db)
; #pragma unroll
;                 for (int s = 0; s < 2; ++s) vf[db][s] = *(const LAS bf16x8_t*)(Vl + (32 * db + r) * AT_VP + (32 * kt + 16 * s + 8 * hh) * 2);
; #pragma unroll
;             for (int cb = 0; cb < 2; ++cb) {
;                 const int dq = 32 * kt - (q0 + 32 * cb);
;                 if ((c == 0 && dq < 0) || (c == 2 && dq > 0)) continue;
;                 const bool diag = (c == 0 || c == 2) && dq == 0;
;                 f32x16 st = MFMA32(kf[0], qf[cb][0], negm);
;                 st = MFMA32(kf[1], qf[cb][1], st); st = MFMA32(kf[2], qf[cb][2], st); st = MFMA32(kf[3], qf[cb][3], st);
;                 float p[16];
; #pragma unroll
;                 for (int i = 0; i < 16; ++i) p[i] = __builtin_amdgcn_exp2f(st[i]);
;                 if (diag) {
;                     const int thr = r - 4 * hh;
; #pragma unroll
;                     for (int i = 0; i < 16; ++i) { const bool vis = c == 0 ? crow(i, 0) >= thr : crow(i, 0) <= thr; p[i] = vis ? p[i] : 0.f; }
;                 }
;                 float s4 = 0.f;
; #pragma unroll
;                 for (int i = 0; i < 16; ++i) s4 += p[i];
;                 rs[cb] += s4;
; #pragma unroll
;                 for (int s = 0; s < 2; ++s) {
;                     u32x4 w; w.x = cvtpk(p[8 * s], p[8 * s + 1]); w.y = cvtpk(p[8 * s + 2], p[8 * s + 3]); w.z = cvtpk(p[8 * s + 4], p[8 * s + 5]); w.w = cvtpk(p[8 * s + 6], p[8 * s + 7]);
;                     const bf16x8_t pb = __builtin_bit_cast(bf16x8_t, w);
;                     o[0][cb] = MFMA32(vf[0][s], pb, o[0][cb]); o[1][cb] = MFMA32(vf[1][s], pb, o[1][cb]);
;                 }
;             }
;         }
	v_mfma_f32_32x32x16_bf16 v[98:113], v[238:241], v[114:117], v[18:33]
	v_exp_f32_e32 v97, v97
	v_add_f32_e32 v182, v82, v182
	v_add_f32_e32 v182, v83, v182
	v_add_f32_e32 v182, v84, v182
	v_add_f32_e32 v182, v85, v182
	v_mfma_f32_32x32x16_bf16 v[98:113], v[242:245], v[118:121], v[98:113]
	v_add_f32_e32 v182, v86, v182
	v_add_f32_e32 v182, v87, v182
	v_add_f32_e32 v182, v88, v182
	v_add_f32_e32 v182, v89, v182
	v_add_f32_e32 v182, v90, v182
	v_mfma_f32_32x32x16_bf16 v[98:113], v[246:249], v[122:125], v[98:113]
	v_add_f32_e32 v182, v91, v182
	v_add_f32_e32 v182, v92, v182
	v_add_f32_e32 v182, v93, v182
	v_add_f32_e32 v182, v94, v182
	v_add_f32_e32 v182, v95, v182
	v_mfma_f32_32x32x16_bf16 v[98:113], v[204:207], v[126:129], v[98:113]
	v_add_f32_e32 v182, v96, v182
	v_add_f32_e32 v182, v97, v182
	v_cvt_pk_bf16_f32 v82, v82, v83
	v_cvt_pk_bf16_f32 v83, v84, v85
	v_cvt_pk_bf16_f32 v84, v86, v87
	v_cvt_pk_bf16_f32 v85, v88, v89
	v_cvt_pk_bf16_f32 v86, v90, v91
	v_cvt_pk_bf16_f32 v87, v92, v93
	v_cvt_pk_bf16_f32 v88, v94, v95
	v_cvt_pk_bf16_f32 v89, v96, v97
	s_nop 0
	s_waitcnt lgkmcnt(0)
	v_mfma_f32_32x32x16_bf16 v[34:49], v[146:149], v[82:85], v[34:49]
	v_mfma_f32_32x32x16_bf16 v[2:17], v[154:157], v[82:85], v[2:17]
	v_exp_f32_e32 v98, v98
	v_exp_f32_e32 v99, v99
	v_exp_f32_e32 v100, v100
	v_exp_f32_e32 v101, v101
	v_exp_f32_e32 v102, v102
	v_mfma_f32_32x32x16_bf16 v[34:49], v[150:153], v[86:89], v[34:49]
	v_exp_f32_e32 v103, v103
	v_exp_f32_e32 v104, v104
	v_exp_f32_e32 v105, v105
	v_exp_f32_e32 v106, v106
	v_exp_f32_e32 v107, v107
	v_mfma_f32_32x32x16_bf16 v[2:17], v[158:161], v[86:89], v[2:17]
	ds_read_b128 v[146:149], v195 offset:192
	ds_read_b128 v[150:153], v195 offset:224
	ds_read_b128 v[154:157], v194 offset:192
	ds_read_b128 v[158:161], v194 offset:224
	v_exp_f32_e32 v108, v108
	v_exp_f32_e32 v109, v109
	v_exp_f32_e32 v110, v110
	v_exp_f32_e32 v111, v111
	v_exp_f32_e32 v112, v112
	s_waitcnt lgkmcnt(0)
	v_mfma_f32_32x32x16_bf16 v[82:97], v[238:241], v[130:133], v[18:33]
	v_exp_f32_e32 v113, v113
	v_add_f32_e32 v183, v98, v183
	v_add_f32_e32 v183, v99, v183
	v_add_f32_e32 v183, v100, v183
	v_add_f32_e32 v183, v101, v183
	v_mfma_f32_32x32x16_bf16 v[82:97], v[242:245], v[134:137], v[82:97]
	v_add_f32_e32 v183, v102, v183
	v_add_f32_e32 v183, v103, v183
	v_add_f32_e32 v183, v104, v183
	v_add_f32_e32 v183, v105, v183
	v_add_f32_e32 v183, v106, v183
	v_mfma_f32_32x32x16_bf16 v[82:97], v[246:249], v[138:141], v[82:97]
	v_add_f32_e32 v183, v107, v183
	v_add_f32_e32 v183, v108, v183
	v_add_f32_e32 v183, v109, v183
	v_add_f32_e32 v183, v110, v183
	v_add_f32_e32 v183, v111, v183
	v_mfma_f32_32x32x16_bf16 v[82:97], v[204:207], v[142:145], v[82:97]
	v_add_f32_e32 v183, v112, v183
	v_add_f32_e32 v183, v113, v183
	v_cvt_pk_bf16_f32 v98, v98, v99
	v_cvt_pk_bf16_f32 v99, v100, v101
	v_cvt_pk_bf16_f32 v100, v102, v103
	v_cvt_pk_bf16_f32 v101, v104, v105
	v_cvt_pk_bf16_f32 v102, v106, v107
	v_cvt_pk_bf16_f32 v103, v108, v109
	v_cvt_pk_bf16_f32 v104, v110, v111
	v_cvt_pk_bf16_f32 v105, v112, v113
	s_nop 0
	s_waitcnt lgkmcnt(0)
	v_mfma_f32_32x32x16_bf16 v[66:81], v[146:149], v[98:101], v[66:81]
	v_mfma_f32_32x32x16_bf16 v[50:65], v[154:157], v[98:101], v[50:65]
	v_exp_f32_e32 v82, v82
	v_exp_f32_e32 v83, v83
	v_exp_f32_e32 v84, v84
	v_exp_f32_e32 v85, v85
	v_exp_f32_e32 v86, v86
	v_mfma_f32_32x32x16_bf16 v[66:81], v[150:153], v[102:105], v[66:81]
	v_exp_f32_e32 v87, v87
	v_exp_f32_e32 v88, v88
	v_exp_f32_e32 v89, v89
	v_exp_f32_e32 v90, v90
	v_exp_f32_e32 v91, v91
	v_mfma_f32_32x32x16_bf16 v[50:65], v[158:161], v[102:105], v[50:65]
	v_exp_f32_e32 v92, v92
	v_exp_f32_e32 v93, v93
	v_exp_f32_e32 v94, v94
	v_exp_f32_e32 v95, v95
	v_exp_f32_e32 v96, v96
	v_exp_f32_e32 v97, v97
	v_add_f32_e32 v182, v82, v182
	v_add_f32_e32 v182, v83, v182
	v_add_f32_e32 v182, v84, v182
	v_add_f32_e32 v182, v85, v182
	v_add_f32_e32 v182, v86, v182
	v_add_f32_e32 v182, v87, v182
	v_add_f32_e32 v182, v88, v182
	v_add_f32_e32 v182, v89, v182
	v_add_f32_e32 v182, v90, v182
	v_add_f32_e32 v182, v91, v182
	v_add_f32_e32 v182, v92, v182
	v_add_f32_e32 v182, v93, v182
	v_add_f32_e32 v182, v94, v182
	v_add_f32_e32 v182, v95, v182
	v_add_f32_e32 v182, v96, v182
	v_add_f32_e32 v182, v97, v182
	v_cvt_pk_bf16_f32 v82, v82, v83
	v_cvt_pk_bf16_f32 v83, v84, v85
	v_cvt_pk_bf16_f32 v84, v86, v87
	v_cvt_pk_bf16_f32 v85, v88, v89
	v_cvt_pk_bf16_f32 v86, v90, v91
	v_cvt_pk_bf16_f32 v87, v92, v93
	v_cvt_pk_bf16_f32 v88, v94, v95
	v_cvt_pk_bf16_f32 v89, v96, v97
	s_nop 1
	s_waitcnt lgkmcnt(0)
	v_mfma_f32_32x32x16_bf16 v[34:49], v[146:149], v[82:85], v[34:49]
	v_mfma_f32_32x32x16_bf16 v[2:17], v[154:157], v[82:85], v[2:17]
	v_mfma_f32_32x32x16_bf16 v[34:49], v[150:153], v[86:89], v[34:49]
	v_mfma_f32_32x32x16_bf16 v[2:17], v[158:161], v[86:89], v[2:17]
	s_branch .LBB9_349
; __device__ __forceinline__ unsigned cvtpk(float lo, float hi) { f32x2_t v = {lo, hi}; bf16x2_t b = __builtin_convertvector(v, bf16x2_t); return __builtin_bit_cast(unsigned, b); }
; __device__ __forceinline__ bool attn_unit(const Ptrs& P, LAS unsigned char* lds, int unit, int tid, int wave, int lane, bool pre, int nxt) {
;     ...
;         for (int kt = 0; kt < 4; ++kt) {
;             if (c == 0 && 32 * kt + 31 < q0) continue;
;             if (c == 2 && 32 * kt > q0 + 63) continue;
;             bf16x8_t kf[4], vf[2][2];
; #pragma unroll
;             for (int ds = 0; ds < 4; ++ds) kf[ds] = *(const LAS bf16x8_t*)(Kl + (32 * kt + r) * AT_KP + (16 * ds + 8 * hh) * 2);
; #pragma unroll
;             for (int db = 0; db < 2; ++db)
; #pragma unroll
;                 for (int s = 0; s < 2; ++s) vf[db][s] = *(const LAS bf16x8_t*)(Vl + (32 * db + r) * AT_VP + (32 * kt + 16 * s + 8 * hh) * 2);
; #pragma unroll
;             for (int cb = 0; cb < 2; ++cb) {
;                 const int dq = 32 * kt - (q0 + 32 * cb);
;                 if ((c == 0 && dq < 0) || (c == 2 && dq > 0)) continue;
;                 const bool diag = (c == 0 || c == 2) && dq == 0;
;                 f32x16 st = MFMA32(kf[0], qf[cb][0], negm);
;                 st = MFMA32(kf[1], qf[cb][1], st); st = MFMA32(kf[2], qf[cb][2], st); st = MFMA32(kf[3], qf[cb][3], st);
;                 float p[16];
; #pragma unroll
;                 for (int i = 0; i < 16; ++i) p[i] = __builtin_amdgcn_exp2f(st[i]);
;                 if (diag) {
;                     const int thr = r - 4 * hh;
; #pragma unroll
;                     for (int i = 0; i < 16; ++i) { const bool vis = c == 0 ? crow(i, 0) >= thr : crow(i, 0) <= thr; p[i] = vis ? p[i] : 0.f; }
;                 }
;                 float s4 = 0.f;
; #pragma unroll
;                 for (int i = 0; i < 16; ++i) s4 += p[i];
;                 rs[cb] += s4;
; #pragma unroll
;                 for (int s = 0; s < 2; ++s) {
;                     u32x4 w; w.x = cvtpk(p[8 * s], p[8 * s + 1]); w.y = cvtpk(p[8 * s + 2], p[8 * s + 3]); w.z = cvtpk(p[8 * s + 4], p[8 * s + 5]); w.w = cvtpk(p[8 * s + 6], p[8 * s + 7]);
;                     const bf16x8_t pb = __builtin_bit_cast(bf16x8_t, w);
;                     o[0][cb] = MFMA32(vf[0][s], pb, o[0][cb]); o[1][cb] = MFMA32(vf[1][s], pb, o[1][cb]);
;                 }
;             }
;         }
.Lam0_hi:
	ds_read_b128 v[238:241], v196 offset:9216
	ds_read_b128 v[242:245], v196 offset:9248
	ds_read_b128 v[246:249], v196 offset:9280
	ds_read_b128 v[204:207], v196 offset:9312
	s_waitcnt lgkmcnt(0)
	v_mfma_f32_32x32x16_bf16 v[82:97], v[238:241], v[114:117], v[18:33]
	v_mfma_f32_32x32x16_bf16 v[82:97], v[242:245], v[118:121], v[82:97]
	v_mfma_f32_32x32x16_bf16 v[82:97], v[246:249], v[122:125], v[82:97]
	v_mfma_f32_32x32x16_bf16 v[82:97], v[204:207], v[126:129], v[82:97]
	ds_read_b128 v[238:241], v196 offset:13824
	ds_read_b128 v[242:245], v196 offset:13856
	ds_read_b128 v[246:249], v196 offset:13888
	ds_read_b128 v[204:207], v196 offset:13920
	s_waitcnt lgkmcnt(0)
	v_mfma_f32_32x32x16_bf16 v[98:113], v[238:241], v[114:117], v[18:33]
	v_mfma_f32_32x32x16_bf16 v[98:113], v[242:245], v[118:121], v[98:113]
	v_mfma_f32_32x32x16_bf16 v[98:113], v[246:249], v[122:125], v[98:113]
	v_mfma_f32_32x32x16_bf16 v[98:113], v[204:207], v[126:129], v[98:113]
	ds_read_b128 v[146:149], v195 offset:128
	ds_read_b128 v[150:153], v195 offset:160
	ds_read_b128 v[154:157], v194 offset:128
	ds_read_b128 v[158:161], v194 offset:160
	s_nop 3
	v_exp_f32_e32 v82, v82
	v_exp_f32_e32 v83, v83
	v_exp_f32_e32 v84, v84
	v_exp_f32_e32 v85, v85
	v_exp_f32_e32 v86, v86
	v_exp_f32_e32 v87, v87
	v_exp_f32_e32 v88, v88
	v_exp_f32_e32 v89, v89
	v_exp_f32_e32 v90, v90
	v_exp_f32_e32 v91, v91
	v_exp_f32_e32 v92, v92
	v_exp_f32_e32 v93, v93
	v_exp_f32_e32 v94, v94
	v_exp_f32_e32 v95, v95
	v_exp_f32_e32 v96, v96
	v_exp_f32_e32 v97, v97
	v_cmp_ge_i32_e32 vcc, 0, v162
	v_cmp_ge_i32_e64 s[98:99], 1, v162
	s_nop 0
	v_cndmask_b32_e32 v82, 0, v82, vcc
	v_cmp_ge_i32_e32 vcc, 2, v162
	v_cndmask_b32_e64 v83, 0, v83, s[98:99]
	v_cmp_ge_i32_e64 s[98:99], 3, v162
	v_cndmask_b32_e32 v84, 0, v84, vcc
	v_cmp_ge_i32_e32 vcc, 8, v162
	v_cndmask_b32_e64 v85, 0, v85, s[98:99]
	v_cmp_ge_i32_e64 s[98:99], 9, v162
	v_cndmask_b32_e32 v86, 0, v86, vcc
	v_cmp_ge_i32_e32 vcc, 10, v162
	v_cndmask_b32_e64 v87, 0, v87, s[98:99]
	v_cmp_ge_i32_e64 s[98:99], 11, v162
	v_cndmask_b32_e32 v88, 0, v88, vcc
	v_cmp_ge_i32_e32 vcc, 16, v162
	v_cndmask_b32_e64 v89, 0, v89, s[98:99]
	v_cmp_ge_i32_e64 s[98:99], 17, v162
	v_cndmask_b32_e32 v90, 0, v90, vcc
	v_cmp_ge_i32_e32 vcc, 18, v162
	v_cndmask_b32_e64 v91, 0, v91, s[98:99]
	v_cmp_ge_i32_e64 s[98:99], 19, v162
	v_cndmask_b32_e32 v92, 0, v92, vcc
	v_cmp_ge_i32_e32 vcc, 24, v162
	v_cndmask_b32_e64 v93, 0, v93, s[98:99]
	v_cmp_ge_i32_e64 s[98:99], 25, v162
	v_cndmask_b32_e32 v94, 0, v94, vcc
	v_cmp_ge_i32_e32 vcc, 26, v162
	v_cndmask_b32_e64 v95, 0, v95, s[98:99]
	v_cmp_ge_i32_e64 s[98:99], 27, v162
	v_cndmask_b32_e32 v96, 0, v96, vcc
	s_nop 0
	v_cndmask_b32_e64 v97, 0, v97, s[98:99]
	s_nop 0
	v_add_f32_e32 v183, v82, v183
	v_add_f32_e32 v183, v83, v183
	v_add_f32_e32 v183, v84, v183
	v_add_f32_e32 v183, v85, v183
	v_add_f32_e32 v183, v86, v183
	v_add_f32_e32 v183, v87, v183
	v_add_f32_e32 v183, v88, v183
	v_add_f32_e32 v183, v89, v183
	v_add_f32_e32 v183, v90, v183
	v_add_f32_e32 v183, v91, v183
	v_add_f32_e32 v183, v92, v183
	v_add_f32_e32 v183, v93, v183
	v_add_f32_e32 v183, v94, v183
	v_add_f32_e32 v183, v95, v183
	v_add_f32_e32 v183, v96, v183
	v_add_f32_e32 v183, v97, v183
	v_cvt_pk_bf16_f32 v82, v82, v83
	v_cvt_pk_bf16_f32 v83, v84, v85
	v_cvt_pk_bf16_f32 v84, v86, v87
	v_cvt_pk_bf16_f32 v85, v88, v89
	v_cvt_pk_bf16_f32 v86, v90, v91
	v_cvt_pk_bf16_f32 v87, v92, v93
	v_cvt_pk_bf16_f32 v88, v94, v95
	v_cvt_pk_bf16_f32 v89, v96, v97
	s_nop 0
	s_waitcnt lgkmcnt(0)
	v_mfma_f32_32x32x16_bf16 v[66:81], v[146:149], v[82:85], v[66:81]
	v_mfma_f32_32x32x16_bf16 v[50:65], v[154:157], v[82:85], v[50:65]
	v_exp_f32_e32 v98, v98
	v_exp_f32_e32 v99, v99
	v_exp_f32_e32 v100, v100
	v_exp_f32_e32 v101, v101
	v_exp_f32_e32 v102, v102
	v_mfma_f32_32x32x16_bf16 v[66:81], v[150:153], v[86:89], v[66:81]
	v_exp_f32_e32 v103, v103
	v_exp_f32_e32 v104, v104
	v_exp_f32_e32 v105, v105
	v_exp_f32_e32 v106, v106
	v_exp_f32_e32 v107, v107
	v_mfma_f32_32x32x16_bf16 v[50:65], v[158:161], v[86:89], v[50:65]
	ds_read_b128 v[146:149], v195 offset:192
	ds_read_b128 v[150:153], v195 offset:224
	ds_read_b128 v[154:157], v194 offset:192
	ds_read_b128 v[158:161], v194 offset:224
	v_exp_f32_e32 v108, v108
	v_exp_f32_e32 v109, v109
	v_exp_f32_e32 v110, v110
	v_exp_f32_e32 v111, v111
	v_exp_f32_e32 v112, v112
	s_waitcnt lgkmcnt(0)
; __device__ __forceinline__ unsigned cvtpk(float lo, float hi) { f32x2_t v = {lo, hi}; bf16x2_t b = __builtin_convertvector(v, bf16x2_t); return __builtin_bit_cast(unsigned, b); }
; __device__ __forceinline__ bool attn_unit(const Ptrs& P, LAS unsigned char* lds, int unit, int tid, int wave, int lane, bool pre, int nxt) {
;     ...
;         for (int kt = 0; kt < 4; ++kt) {
;             if (c == 0 && 32 * kt + 31 < q0) continue;
;             if (c == 2 && 32 * kt > q0 + 63) continue;
;             bf16x8_t kf[4], vf[2][2];
; #pragma unroll
;             for (int ds = 0; ds < 4; ++ds) kf[ds] = *(const LAS bf16x8_t*)(Kl + (32 * kt + r) * AT_KP + (16 * ds + 8 * hh) * 2);
; #pragma unroll
;             for (int db = 0; db < 2; ++db)
; #pragma unroll
;                 for (int s = 0; s < 2; ++s) vf[db][s] = *(const LAS bf16x8_t*)(Vl + (32 * db + r) * AT_VP + (32 * kt + 16 * s + 8 * hh) * 2);
; #pragma unroll
;             for (int cb = 0; cb < 2; ++cb) {
;                 const int dq = 32 * kt - (q0 + 32 * cb);
;                 if ((c == 0 && dq < 0) || (c == 2 && dq > 0)) continue;
;                 const bool diag = (c == 0 || c == 2) && dq == 0;
;                 f32x16 st = MFMA32(kf[0], qf[cb][0], negm);
;                 st = MFMA32(kf[1], qf[cb][1], st); st = MFMA32(kf[2], qf[cb][2], st); st = MFMA32(kf[3], qf[cb][3], st);
;                 float p[16];
; #pragma unroll
;                 for (int i = 0; i < 16; ++i) p[i] = __builtin_amdgcn_exp2f(st[i]);
;                 if (diag) {
;                     const int thr = r - 4 * hh;
; #pragma unroll
;                     for (int i = 0; i < 16; ++i) { const bool vis = c == 0 ? crow(i, 0) >= thr : crow(i, 0) <= thr; p[i] = vis ? p[i] : 0.f; }
;                 }
;                 float s4 = 0.f;
; #pragma unroll
;                 for (int i = 0; i < 16; ++i) s4 += p[i];
;                 rs[cb] += s4;
; #pragma unroll
;                 for (int s = 0; s < 2; ++s) {
;                     u32x4 w; w.x = cvtpk(p[8 * s], p[8 * s + 1]); w.y = cvtpk(p[8 * s + 2], p[8 * s + 3]); w.z = cvtpk(p[8 * s + 4], p[8 * s + 5]); w.w = cvtpk(p[8 * s + 6], p[8 * s + 7]);
;                     const bf16x8_t pb = __builtin_bit_cast(bf16x8_t, w);
;                     o[0][cb] = MFMA32(vf[0][s], pb, o[0][cb]); o[1][cb] = MFMA32(vf[1][s], pb, o[1][cb]);
;                 }
;             }
;         }
	v_mfma_f32_32x32x16_bf16 v[82:97], v[238:241], v[130:133], v[18:33]
	v_exp_f32_e32 v113, v113
	v_add_f32_e32 v183, v98, v183
	v_add_f32_e32 v183, v99, v183
	v_add_f32_e32 v183, v100, v183
	v_add_f32_e32 v183, v101, v183
	v_mfma_f32_32x32x16_bf16 v[82:97], v[242:245], v[134:137], v[82:97]
	v_add_f32_e32 v183, v102, v183
	v_add_f32_e32 v183, v103, v183
	v_add_f32_e32 v183, v104, v183
	v_add_f32_e32 v183, v105, v183
	v_add_f32_e32 v183, v106, v183
	v_mfma_f32_32x32x16_bf16 v[82:97], v[246:249], v[138:141], v[82:97]
	v_add_f32_e32 v183, v107, v183
	v_add_f32_e32 v183, v108, v183
	v_add_f32_e32 v183, v109, v183
	v_add_f32_e32 v183, v110, v183
	v_add_f32_e32 v183, v111, v183
	v_mfma_f32_32x32x16_bf16 v[82:97], v[204:207], v[142:145], v[82:97]
	v_add_f32_e32 v183, v112, v183
	v_add_f32_e32 v183, v113, v183
	v_cvt_pk_bf16_f32 v98, v98, v99
	v_cvt_pk_bf16_f32 v99, v100, v101
	v_cvt_pk_bf16_f32 v100, v102, v103
	v_cvt_pk_bf16_f32 v101, v104, v105
	v_cvt_pk_bf16_f32 v102, v106, v107
	v_cvt_pk_bf16_f32 v103, v108, v109
	v_cvt_pk_bf16_f32 v104, v110, v111
	v_cvt_pk_bf16_f32 v105, v112, v113
	s_nop 0
	s_waitcnt lgkmcnt(0)
	v_mfma_f32_32x32x16_bf16 v[66:81], v[146:149], v[98:101], v[66:81]
	v_mfma_f32_32x32x16_bf16 v[50:65], v[154:157], v[98:101], v[50:65]
	v_exp_f32_e32 v82, v82
	v_exp_f32_e32 v83, v83
	v_exp_f32_e32 v84, v84
	v_exp_f32_e32 v85, v85
	v_exp_f32_e32 v86, v86
	v_mfma_f32_32x32x16_bf16 v[66:81], v[150:153], v[102:105], v[66:81]
	v_exp_f32_e32 v87, v87
	v_exp_f32_e32 v88, v88
	v_exp_f32_e32 v89, v89
	v_exp_f32_e32 v90, v90
	v_exp_f32_e32 v91, v91
	v_mfma_f32_32x32x16_bf16 v[50:65], v[158:161], v[102:105], v[50:65]
	v_exp_f32_e32 v92, v92
	v_exp_f32_e32 v93, v93
	v_exp_f32_e32 v94, v94
	v_exp_f32_e32 v95, v95
	v_exp_f32_e32 v96, v96
	v_exp_f32_e32 v97, v97
	v_cmp_ge_i32_e32 vcc, 0, v162
	v_cmp_ge_i32_e64 s[98:99], 1, v162
	s_nop 0
	v_cndmask_b32_e32 v82, 0, v82, vcc
	v_cmp_ge_i32_e32 vcc, 2, v162
	v_cndmask_b32_e64 v83, 0, v83, s[98:99]
	v_cmp_ge_i32_e64 s[98:99], 3, v162
	v_cndmask_b32_e32 v84, 0, v84, vcc
	v_cmp_ge_i32_e32 vcc, 8, v162
	v_cndmask_b32_e64 v85, 0, v85, s[98:99]
	v_cmp_ge_i32_e64 s[98:99], 9, v162
	v_cndmask_b32_e32 v86, 0, v86, vcc
	v_cmp_ge_i32_e32 vcc, 10, v162
	v_cndmask_b32_e64 v87, 0, v87, s[98:99]
	v_cmp_ge_i32_e64 s[98:99], 11, v162
	v_cndmask_b32_e32 v88, 0, v88, vcc
	v_cmp_ge_i32_e32 vcc, 16, v162
	v_cndmask_b32_e64 v89, 0, v89, s[98:99]
	v_cmp_ge_i32_e64 s[98:99], 17, v162
	v_cndmask_b32_e32 v90, 0, v90, vcc
	v_cmp_ge_i32_e32 vcc, 18, v162
	v_cndmask_b32_e64 v91, 0, v91, s[98:99]
	v_cmp_ge_i32_e64 s[98:99], 19, v162
	v_cndmask_b32_e32 v92, 0, v92, vcc
	v_cmp_ge_i32_e32 vcc, 24, v162
	v_cndmask_b32_e64 v93, 0, v93, s[98:99]
	v_cmp_ge_i32_e64 s[98:99], 25, v162
	v_cndmask_b32_e32 v94, 0, v94, vcc
	v_cmp_ge_i32_e32 vcc, 26, v162
	v_cndmask_b32_e64 v95, 0, v95, s[98:99]
	v_cmp_ge_i32_e64 s[98:99], 27, v162
	v_cndmask_b32_e32 v96, 0, v96, vcc
	s_nop 0
	v_cndmask_b32_e64 v97, 0, v97, s[98:99]
	s_nop 0
	v_add_f32_e32 v182, v82, v182
	v_add_f32_e32 v182, v83, v182
	v_add_f32_e32 v182, v84, v182
	v_add_f32_e32 v182, v85, v182
	v_add_f32_e32 v182, v86, v182
	v_add_f32_e32 v182, v87, v182
	v_add_f32_e32 v182, v88, v182
	v_add_f32_e32 v182, v89, v182
	v_add_f32_e32 v182, v90, v182
	v_add_f32_e32 v182, v91, v182
	v_add_f32_e32 v182, v92, v182
	v_add_f32_e32 v182, v93, v182
	v_add_f32_e32 v182, v94, v182
	v_add_f32_e32 v182, v95, v182
	v_add_f32_e32 v182, v96, v182
	v_add_f32_e32 v182, v97, v182
	v_cvt_pk_bf16_f32 v82, v82, v83
	v_cvt_pk_bf16_f32 v83, v84, v85
	v_cvt_pk_bf16_f32 v84, v86, v87
	v_cvt_pk_bf16_f32 v85, v88, v89
	v_cvt_pk_bf16_f32 v86, v90, v91
	v_cvt_pk_bf16_f32 v87, v92, v93
	v_cvt_pk_bf16_f32 v88, v94, v95
	v_cvt_pk_bf16_f32 v89, v96, v97
	s_nop 1
	s_waitcnt lgkmcnt(0)
	v_mfma_f32_32x32x16_bf16 v[34:49], v[146:149], v[82:85], v[34:49]
	v_mfma_f32_32x32x16_bf16 v[2:17], v[154:157], v[82:85], v[2:17]
	v_mfma_f32_32x32x16_bf16 v[34:49], v[150:153], v[86:89], v[34:49]
	v_mfma_f32_32x32x16_bf16 v[2:17], v[158:161], v[86:89], v[2:17]

; #define LAS __attribute__((address_space(3)))
; __device__ __forceinline__ bool attn_unit(const Ptrs& P, LAS unsigned char* lds, int unit, int tid, int wave, int lane, bool pre, int nxt) {
;     ...
;         const LAS unsigned char* Kl = lds + (c % 3) * AT_BUF; const LAS unsigned char* Vl = Kl + AT_KB;
; #pragma unroll 1
;         for (int kt = 0; kt < 4; ++kt) {
;             if (c == 0 && 32 * kt + 31 < q0) continue;
;             if (c == 2 && 32 * kt > q0 + 63) continue;
;             bf16x8_t kf[4], vf[2][2];
; #pragma unroll
;             for (int ds = 0; ds < 4; ++ds) kf[ds] = *(const LAS bf16x8_t*)(Kl + (32 * kt + r) * AT_KP + (16 * ds + 8 * hh) * 2);
; #pragma unroll
;             for (int db = 0; db < 2; ++db)
; #pragma unroll
;                 for (int s = 0; s < 2; ++s) vf[db][s] = *(const LAS bf16x8_t*)(Vl + (32 * db + r) * AT_VP + (32 * kt + 16 * s + 8 * hh) * 2);
; #pragma unroll
;             for (int cb = 0; cb < 2; ++cb) {
;                 const int dq = 32 * kt - (q0 + 32 * cb);
;                 if ((c == 0 && dq < 0) || (c == 2 && dq > 0)) continue;
;                 const bool diag = (c == 0 || c == 2) && dq == 0;
;                 f32x16 st = MFMA32(kf[0], qf[cb][0], negm);
;                 st = MFMA32(kf[1], qf[cb][1], st); st = MFMA32(kf[2], qf[cb][2], st); st = MFMA32(kf[3], qf[cb][3], st);
;                 float p[16];
; #pragma unroll
;                 for (int i = 0; i < 16; ++i) p[i] = __builtin_amdgcn_exp2f(st[i]);
;                 if (diag) {
;                     const int thr = r - 4 * hh;
; #pragma unroll
;                     for (int i = 0; i < 16; ++i) { const bool vis = c == 0 ? crow(i, 0) >= thr : crow(i, 0) <= thr; p[i] = vis ? p[i] : 0.f; }
;                 }
;                 float s4 = 0.f;
; #pragma unroll
;                 for (int i = 0; i < 16; ++i) s4 += p[i];
;                 rs[cb] += s4;
; #pragma unroll
;                 for (int s = 0; s < 2; ++s) {
;                     u32x4 w; w.x = cvtpk(p[8 * s], p[8 * s + 1]); w.y = cvtpk(p[8 * s + 2], p[8 * s + 3]); w.z = cvtpk(p[8 * s + 4], p[8 * s + 5]); w.w = cvtpk(p[8 * s + 6], p[8 * s + 7]);
;                     const bf16x8_t pb = __builtin_bit_cast(bf16x8_t, w);
;                     o[0][cb] = MFMA32(vf[0][s], pb, o[0][cb]); o[1][cb] = MFMA32(vf[1][s], pb, o[1][cb]);
;                 }
;             }
;         }
.LBB9_382:
	v_and_b32_e32 v162, 31, v170
	v_lshrrev_b32_e32 v163, 5, v170
	v_lshlrev_b32_e32 v163, 2, v163
	v_sub_u32_e32 v162, v162, v163
	v_add_u32_e32 v163, v202, v191
	v_add_u32_e32 v163, 0x11800, v163
	v_add_u32_e32 v164, v201, v191
	v_add_u32_e32 v164, 0x16000, v164
	v_add_u32_e32 v165, v200, v191
	v_add_u32_e32 v165, 0x16000, v165
	s_cmp_eq_u32 s33, 0
	s_cbranch_scc0 .Lam2_hi
	ds_read_b128 v[238:241], v163 offset:0
	ds_read_b128 v[242:245], v163 offset:32
	ds_read_b128 v[246:249], v163 offset:64
	ds_read_b128 v[204:207], v163 offset:96
	s_waitcnt lgkmcnt(0)
	v_mfma_f32_32x32x16_bf16 v[82:97], v[238:241], v[114:117], v[18:33]
	v_mfma_f32_32x32x16_bf16 v[82:97], v[242:245], v[118:121], v[82:97]
	v_mfma_f32_32x32x16_bf16 v[82:97], v[246:249], v[122:125], v[82:97]
	v_mfma_f32_32x32x16_bf16 v[82:97], v[204:207], v[126:129], v[82:97]
	s_waitcnt lgkmcnt(0)
	v_mfma_f32_32x32x16_bf16 v[98:113], v[238:241], v[130:133], v[18:33]
	v_mfma_f32_32x32x16_bf16 v[98:113], v[242:245], v[134:137], v[98:113]
	v_mfma_f32_32x32x16_bf16 v[98:113], v[246:249], v[138:141], v[98:113]
	v_mfma_f32_32x32x16_bf16 v[98:113], v[204:207], v[142:145], v[98:113]
	ds_read_b128 v[146:149], v164 offset:0
	ds_read_b128 v[150:153], v164 offset:32
	ds_read_b128 v[154:157], v165 offset:0
	ds_read_b128 v[158:161], v165 offset:32
	ds_read_b128 v[238:241], v163 offset:4608
	ds_read_b128 v[242:245], v163 offset:4640
	ds_read_b128 v[246:249], v163 offset:4672
	ds_read_b128 v[204:207], v163 offset:4704
	v_exp_f32_e32 v82, v82
	v_exp_f32_e32 v83, v83
	v_exp_f32_e32 v84, v84
	v_exp_f32_e32 v85, v85
	v_exp_f32_e32 v86, v86
	v_exp_f32_e32 v87, v87
	v_exp_f32_e32 v88, v88
	v_exp_f32_e32 v89, v89
	v_exp_f32_e32 v90, v90
	v_exp_f32_e32 v91, v91
	v_exp_f32_e32 v92, v92
	v_exp_f32_e32 v93, v93
	v_exp_f32_e32 v94, v94
	v_exp_f32_e32 v95, v95
	v_exp_f32_e32 v96, v96
	v_exp_f32_e32 v97, v97
	v_cmp_le_i32_e32 vcc, 0, v162
	v_cmp_le_i32_e64 s[98:99], 1, v162
	s_nop 0
	v_cndmask_b32_e32 v82, 0, v82, vcc
	v_cmp_le_i32_e32 vcc, 2, v162
	v_cndmask_b32_e64 v83, 0, v83, s[98:99]
	v_cmp_le_i32_e64 s[98:99], 3, v162
	v_cndmask_b32_e32 v84, 0, v84, vcc
	v_cmp_le_i32_e32 vcc, 8, v162
	v_cndmask_b32_e64 v85, 0, v85, s[98:99]
	v_cmp_le_i32_e64 s[98:99], 9, v162
	v_cndmask_b32_e32 v86, 0, v86, vcc
	v_cmp_le_i32_e32 vcc, 10, v162
	v_cndmask_b32_e64 v87, 0, v87, s[98:99]
	v_cmp_le_i32_e64 s[98:99], 11, v162
	v_cndmask_b32_e32 v88, 0, v88, vcc
	v_cmp_le_i32_e32 vcc, 16, v162
	v_cndmask_b32_e64 v89, 0, v89, s[98:99]
	v_cmp_le_i32_e64 s[98:99], 17, v162
	v_cndmask_b32_e32 v90, 0, v90, vcc
	v_cmp_le_i32_e32 vcc, 18, v162
	v_cndmask_b32_e64 v91, 0, v91, s[98:99]
	v_cmp_le_i32_e64 s[98:99], 19, v162
	v_cndmask_b32_e32 v92, 0, v92, vcc
	v_cmp_le_i32_e32 vcc, 24, v162
	v_cndmask_b32_e64 v93, 0, v93, s[98:99]
	v_cmp_le_i32_e64 s[98:99], 25, v162
	v_cndmask_b32_e32 v94, 0, v94, vcc
	v_cmp_le_i32_e32 vcc, 26, v162
	v_cndmask_b32_e64 v95, 0, v95, s[98:99]
	v_cmp_le_i32_e64 s[98:99], 27, v162
	v_cndmask_b32_e32 v96, 0, v96, vcc
	s_nop 0
	v_cndmask_b32_e64 v97, 0, v97, s[98:99]
	s_nop 0
	v_add_f32_e32 v183, v82, v183
	v_add_f32_e32 v183, v83, v183
	v_add_f32_e32 v183, v84, v183
	v_add_f32_e32 v183, v85, v183
	v_add_f32_e32 v183, v86, v183
	v_add_f32_e32 v183, v87, v183
	v_add_f32_e32 v183, v88, v183
	v_add_f32_e32 v183, v89, v183
	v_add_f32_e32 v183, v90, v183
	v_add_f32_e32 v183, v91, v183
	v_add_f32_e32 v183, v92, v183
	v_add_f32_e32 v183, v93, v183
	v_add_f32_e32 v183, v94, v183
	v_add_f32_e32 v183, v95, v183
	v_add_f32_e32 v183, v96, v183
	v_add_f32_e32 v183, v97, v183
	v_cvt_pk_bf16_f32 v82, v82, v83
	v_cvt_pk_bf16_f32 v83, v84, v85
	v_cvt_pk_bf16_f32 v84, v86, v87
	v_cvt_pk_bf16_f32 v85, v88, v89
	v_cvt_pk_bf16_f32 v86, v90, v91
	v_cvt_pk_bf16_f32 v87, v92, v93
	v_cvt_pk_bf16_f32 v88, v94, v95
	v_cvt_pk_bf16_f32 v89, v96, v97
	s_nop 0
	s_waitcnt lgkmcnt(0)
	v_mfma_f32_32x32x16_bf16 v[66:81], v[146:149], v[82:85], v[66:81]
	v_mfma_f32_32x32x16_bf16 v[50:65], v[154:157], v[82:85], v[50:65]
	v_exp_f32_e32 v98, v98
	v_exp_f32_e32 v99, v99
	v_exp_f32_e32 v100, v100
	v_exp_f32_e32 v101, v101
	v_exp_f32_e32 v102, v102
	v_mfma_f32_32x32x16_bf16 v[66:81], v[150:153], v[86:89], v[66:81]
	v_exp_f32_e32 v103, v103
	v_exp_f32_e32 v104, v104
	v_exp_f32_e32 v105, v105
	v_exp_f32_e32 v106, v106
	v_exp_f32_e32 v107, v107
	v_mfma_f32_32x32x16_bf16 v[50:65], v[158:161], v[86:89], v[50:65]
	v_exp_f32_e32 v108, v108
	v_exp_f32_e32 v109, v109
	v_exp_f32_e32 v110, v110
	v_exp_f32_e32 v111, v111
	v_exp_f32_e32 v112, v112
	s_waitcnt lgkmcnt(0)
	v_mfma_f32_32x32x16_bf16 v[82:97], v[238:241], v[130:133], v[18:33]
	v_exp_f32_e32 v113, v113
	v_add_f32_e32 v182, v98, v182
	v_add_f32_e32 v182, v99, v182
	v_add_f32_e32 v182, v100, v182
	v_add_f32_e32 v182, v101, v182
	v_mfma_f32_32x32x16_bf16 v[82:97], v[242:245], v[134:137], v[82:97]
	v_add_f32_e32 v182, v102, v182
	v_add_f32_e32 v182, v103, v182
	v_add_f32_e32 v182, v104, v182
	v_add_f32_e32 v182, v105, v182
	v_add_f32_e32 v182, v106, v182
	v_mfma_f32_32x32x16_bf16 v[82:97], v[246:249], v[138:141], v[82:97]
	v_add_f32_e32 v182, v107, v182
	v_add_f32_e32 v182, v108, v182
	v_add_f32_e32 v182, v109, v182
	v_add_f32_e32 v182, v110, v182
	v_add_f32_e32 v182, v111, v182
	v_mfma_f32_32x32x16_bf16 v[82:97], v[204:207], v[142:145], v[82:97]
	v_add_f32_e32 v182, v112, v182
	v_add_f32_e32 v182, v113, v182
	v_cvt_pk_bf16_f32 v98, v98, v99
	v_cvt_pk_bf16_f32 v99, v100, v101
	v_cvt_pk_bf16_f32 v100, v102, v103
	v_cvt_pk_bf16_f32 v101, v104, v105
	v_cvt_pk_bf16_f32 v102, v106, v107
	v_cvt_pk_bf16_f32 v103, v108, v109
	v_cvt_pk_bf16_f32 v104, v110, v111
	v_cvt_pk_bf16_f32 v105, v112, v113
	s_nop 0
	s_waitcnt lgkmcnt(0)
; __device__ __forceinline__ unsigned cvtpk(float lo, float hi) { f32x2_t v = {lo, hi}; bf16x2_t b = __builtin_convertvector(v, bf16x2_t); return __builtin_bit_cast(unsigned, b); }
; __device__ __forceinline__ bool attn_unit(const Ptrs& P, LAS unsigned char* lds, int unit, int tid, int wave, int lane, bool pre, int nxt) {
;     ...
;         for (int kt = 0; kt < 4; ++kt) {
;             if (c == 0 && 32 * kt + 31 < q0) continue;
;             if (c == 2 && 32 * kt > q0 + 63) continue;
;             bf16x8_t kf[4], vf[2][2];
; #pragma unroll
;             for (int ds = 0; ds < 4; ++ds) kf[ds] = *(const LAS bf16x8_t*)(Kl + (32 * kt + r) * AT_KP + (16 * ds + 8 * hh) * 2);
; #pragma unroll
;             for (int db = 0; db < 2; ++db)
; #pragma unroll
;                 for (int s = 0; s < 2; ++s) vf[db][s] = *(const LAS bf16x8_t*)(Vl + (32 * db + r) * AT_VP + (32 * kt + 16 * s + 8 * hh) * 2);
; #pragma unroll
;             for (int cb = 0; cb < 2; ++cb) {
;                 const int dq = 32 * kt - (q0 + 32 * cb);
;                 if ((c == 0 && dq < 0) || (c == 2 && dq > 0)) continue;
;                 const bool diag = (c == 0 || c == 2) && dq == 0;
;                 f32x16 st = MFMA32(kf[0], qf[cb][0], negm);
;                 st = MFMA32(kf[1], qf[cb][1], st); st = MFMA32(kf[2], qf[cb][2], st); st = MFMA32(kf[3], qf[cb][3], st);
;                 float p[16];
; #pragma unroll
;                 for (int i = 0; i < 16; ++i) p[i] = __builtin_amdgcn_exp2f(st[i]);
;                 if (diag) {
;                     const int thr = r - 4 * hh;
; #pragma unroll
;                     for (int i = 0; i < 16; ++i) { const bool vis = c == 0 ? crow(i, 0) >= thr : crow(i, 0) <= thr; p[i] = vis ? p[i] : 0.f; }
;                 }
;                 float s4 = 0.f;
; #pragma unroll
;                 for (int i = 0; i < 16; ++i) s4 += p[i];
;                 rs[cb] += s4;
; #pragma unroll
;                 for (int s = 0; s < 2; ++s) {
;                     u32x4 w; w.x = cvtpk(p[8 * s], p[8 * s + 1]); w.y = cvtpk(p[8 * s + 2], p[8 * s + 3]); w.z = cvtpk(p[8 * s + 4], p[8 * s + 5]); w.w = cvtpk(p[8 * s + 6], p[8 * s + 7]);
;                     const bf16x8_t pb = __builtin_bit_cast(bf16x8_t, w);
;                     o[0][cb] = MFMA32(vf[0][s], pb, o[0][cb]); o[1][cb] = MFMA32(vf[1][s], pb, o[1][cb]);
;                 }
;             }
;         }
	v_mfma_f32_32x32x16_bf16 v[34:49], v[146:149], v[98:101], v[34:49]
	v_mfma_f32_32x32x16_bf16 v[2:17], v[154:157], v[98:101], v[2:17]
	v_exp_f32_e32 v82, v82
	v_exp_f32_e32 v83, v83
	v_exp_f32_e32 v84, v84
	v_exp_f32_e32 v85, v85
	v_exp_f32_e32 v86, v86
	v_mfma_f32_32x32x16_bf16 v[34:49], v[150:153], v[102:105], v[34:49]
	v_exp_f32_e32 v87, v87
	v_exp_f32_e32 v88, v88
	v_exp_f32_e32 v89, v89
	v_exp_f32_e32 v90, v90
	v_exp_f32_e32 v91, v91
	v_mfma_f32_32x32x16_bf16 v[2:17], v[158:161], v[102:105], v[2:17]
	ds_read_b128 v[146:149], v164 offset:64
	ds_read_b128 v[150:153], v164 offset:96
	ds_read_b128 v[154:157], v165 offset:64
	ds_read_b128 v[158:161], v165 offset:96
	v_exp_f32_e32 v92, v92
	v_exp_f32_e32 v93, v93
	v_exp_f32_e32 v94, v94
	v_exp_f32_e32 v95, v95
	v_exp_f32_e32 v96, v96
	v_exp_f32_e32 v97, v97
	v_cmp_le_i32_e32 vcc, 0, v162
	v_cmp_le_i32_e64 s[98:99], 1, v162
	s_nop 0
	v_cndmask_b32_e32 v82, 0, v82, vcc
	v_cmp_le_i32_e32 vcc, 2, v162
	v_cndmask_b32_e64 v83, 0, v83, s[98:99]
	v_cmp_le_i32_e64 s[98:99], 3, v162
	v_cndmask_b32_e32 v84, 0, v84, vcc
	v_cmp_le_i32_e32 vcc, 8, v162
	v_cndmask_b32_e64 v85, 0, v85, s[98:99]
	v_cmp_le_i32_e64 s[98:99], 9, v162
	v_cndmask_b32_e32 v86, 0, v86, vcc
	v_cmp_le_i32_e32 vcc, 10, v162
	v_cndmask_b32_e64 v87, 0, v87, s[98:99]
	v_cmp_le_i32_e64 s[98:99], 11, v162
	v_cndmask_b32_e32 v88, 0, v88, vcc
	v_cmp_le_i32_e32 vcc, 16, v162
	v_cndmask_b32_e64 v89, 0, v89, s[98:99]
	v_cmp_le_i32_e64 s[98:99], 17, v162
	v_cndmask_b32_e32 v90, 0, v90, vcc
	v_cmp_le_i32_e32 vcc, 18, v162
	v_cndmask_b32_e64 v91, 0, v91, s[98:99]
	v_cmp_le_i32_e64 s[98:99], 19, v162
	v_cndmask_b32_e32 v92, 0, v92, vcc
	v_cmp_le_i32_e32 vcc, 24, v162
	v_cndmask_b32_e64 v93, 0, v93, s[98:99]
	v_cmp_le_i32_e64 s[98:99], 25, v162
	v_cndmask_b32_e32 v94, 0, v94, vcc
	v_cmp_le_i32_e32 vcc, 26, v162
	v_cndmask_b32_e64 v95, 0, v95, s[98:99]
	v_cmp_le_i32_e64 s[98:99], 27, v162
	v_cndmask_b32_e32 v96, 0, v96, vcc
	s_nop 0
	v_cndmask_b32_e64 v97, 0, v97, s[98:99]
	s_nop 0
	v_add_f32_e32 v182, v82, v182
	v_add_f32_e32 v182, v83, v182
	v_add_f32_e32 v182, v84, v182
	v_add_f32_e32 v182, v85, v182
	v_add_f32_e32 v182, v86, v182
	v_add_f32_e32 v182, v87, v182
	v_add_f32_e32 v182, v88, v182
	v_add_f32_e32 v182, v89, v182
	v_add_f32_e32 v182, v90, v182
	v_add_f32_e32 v182, v91, v182
	v_add_f32_e32 v182, v92, v182
	v_add_f32_e32 v182, v93, v182
	v_add_f32_e32 v182, v94, v182
	v_add_f32_e32 v182, v95, v182
	v_add_f32_e32 v182, v96, v182
	v_add_f32_e32 v182, v97, v182
	v_cvt_pk_bf16_f32 v82, v82, v83
	v_cvt_pk_bf16_f32 v83, v84, v85
	v_cvt_pk_bf16_f32 v84, v86, v87
	v_cvt_pk_bf16_f32 v85, v88, v89
	v_cvt_pk_bf16_f32 v86, v90, v91
	v_cvt_pk_bf16_f32 v87, v92, v93
	v_cvt_pk_bf16_f32 v88, v94, v95
	v_cvt_pk_bf16_f32 v89, v96, v97
	s_nop 1
	s_waitcnt lgkmcnt(0)
	v_mfma_f32_32x32x16_bf16 v[34:49], v[146:149], v[82:85], v[34:49]
	v_mfma_f32_32x32x16_bf16 v[2:17], v[154:157], v[82:85], v[2:17]
	v_mfma_f32_32x32x16_bf16 v[34:49], v[150:153], v[86:89], v[34:49]
	v_mfma_f32_32x32x16_bf16 v[2:17], v[158:161], v[86:89], v[2:17]
	s_branch .LBB9_390
.Lam2_hi:
	ds_read_b128 v[238:241], v163 offset:0
	ds_read_b128 v[242:245], v163 offset:32
	ds_read_b128 v[246:249], v163 offset:64
	ds_read_b128 v[204:207], v163 offset:96
	s_waitcnt lgkmcnt(0)
	v_mfma_f32_32x32x16_bf16 v[82:97], v[238:241], v[114:117], v[18:33]
	v_mfma_f32_32x32x16_bf16 v[82:97], v[242:245], v[118:121], v[82:97]
	v_mfma_f32_32x32x16_bf16 v[82:97], v[246:249], v[122:125], v[82:97]
	v_mfma_f32_32x32x16_bf16 v[82:97], v[204:207], v[126:129], v[82:97]
	s_waitcnt lgkmcnt(0)
	v_mfma_f32_32x32x16_bf16 v[98:113], v[238:241], v[130:133], v[18:33]
	v_mfma_f32_32x32x16_bf16 v[98:113], v[242:245], v[134:137], v[98:113]
	v_mfma_f32_32x32x16_bf16 v[98:113], v[246:249], v[138:141], v[98:113]
	v_mfma_f32_32x32x16_bf16 v[98:113], v[204:207], v[142:145], v[98:113]
	ds_read_b128 v[146:149], v164 offset:0
	ds_read_b128 v[150:153], v164 offset:32
	ds_read_b128 v[154:157], v165 offset:0
	ds_read_b128 v[158:161], v165 offset:32
	ds_read_b128 v[238:241], v163 offset:4608
	ds_read_b128 v[242:245], v163 offset:4640
	ds_read_b128 v[246:249], v163 offset:4672
	ds_read_b128 v[204:207], v163 offset:4704
	v_exp_f32_e32 v82, v82
	v_exp_f32_e32 v83, v83
	v_exp_f32_e32 v84, v84
	v_exp_f32_e32 v85, v85
	v_exp_f32_e32 v86, v86
	v_exp_f32_e32 v87, v87
	v_exp_f32_e32 v88, v88
	v_exp_f32_e32 v89, v89
	v_exp_f32_e32 v90, v90
	v_exp_f32_e32 v91, v91
	v_exp_f32_e32 v92, v92
	v_exp_f32_e32 v93, v93
	v_exp_f32_e32 v94, v94
	v_exp_f32_e32 v95, v95
	v_exp_f32_e32 v96, v96
	v_exp_f32_e32 v97, v97
	v_add_f32_e32 v183, v82, v183
	v_add_f32_e32 v183, v83, v183
	v_add_f32_e32 v183, v84, v183
	v_add_f32_e32 v183, v85, v183
	v_add_f32_e32 v183, v86, v183
	v_add_f32_e32 v183, v87, v183
	v_add_f32_e32 v183, v88, v183
	v_add_f32_e32 v183, v89, v183
	v_add_f32_e32 v183, v90, v183
	v_add_f32_e32 v183, v91, v183
	v_add_f32_e32 v183, v92, v183
	v_add_f32_e32 v183, v93, v183
	v_add_f32_e32 v183, v94, v183
	v_add_f32_e32 v183, v95, v183
	v_add_f32_e32 v183, v96, v183
	v_add_f32_e32 v183, v97, v183
	v_cvt_pk_bf16_f32 v82, v82, v83
	v_cvt_pk_bf16_f32 v83, v84, v85
	v_cvt_pk_bf16_f32 v84, v86, v87
	v_cvt_pk_bf16_f32 v85, v88, v89
	v_cvt_pk_bf16_f32 v86, v90, v91
	v_cvt_pk_bf16_f32 v87, v92, v93
	v_cvt_pk_bf16_f32 v88, v94, v95
	v_cvt_pk_bf16_f32 v89, v96, v97
	s_nop 0
	s_waitcnt lgkmcnt(0)
; __device__ __forceinline__ unsigned cvtpk(float lo, float hi) { f32x2_t v = {lo, hi}; bf16x2_t b = __builtin_convertvector(v, bf16x2_t); return __builtin_bit_cast(unsigned, b); }
; #define LAS __attribute__((address_space(3)))
; __device__ __forceinline__ bool attn_unit(const Ptrs& P, LAS unsigned char* lds, int unit, int tid, int wave, int lane, bool pre, int nxt) {
;     ...
;         for (int kt = 0; kt < 4; ++kt) {
;             if (c == 0 && 32 * kt + 31 < q0) continue;
;             if (c == 2 && 32 * kt > q0 + 63) continue;
;             bf16x8_t kf[4], vf[2][2];
; #pragma unroll
;             for (int ds = 0; ds < 4; ++ds) kf[ds] = *(const LAS bf16x8_t*)(Kl + (32 * kt + r) * AT_KP + (16 * ds + 8 * hh) * 2);
; #pragma unroll
;             for (int db = 0; db < 2; ++db)
; #pragma unroll
;                 for (int s = 0; s < 2; ++s) vf[db][s] = *(const LAS bf16x8_t*)(Vl + (32 * db + r) * AT_VP + (32 * kt + 16 * s + 8 * hh) * 2);
; #pragma unroll
;             for (int cb = 0; cb < 2; ++cb) {
;                 const int dq = 32 * kt - (q0 + 32 * cb);
;                 if ((c == 0 && dq < 0) || (c == 2 && dq > 0)) continue;
;                 const bool diag = (c == 0 || c == 2) && dq == 0;
;                 f32x16 st = MFMA32(kf[0], qf[cb][0], negm);
;                 st = MFMA32(kf[1], qf[cb][1], st); st = MFMA32(kf[2], qf[cb][2], st); st = MFMA32(kf[3], qf[cb][3], st);
;                 float p[16];
; #pragma unroll
;                 for (int i = 0; i < 16; ++i) p[i] = __builtin_amdgcn_exp2f(st[i]);
;                 if (diag) {
;                     const int thr = r - 4 * hh;
; #pragma unroll
;                     for (int i = 0; i < 16; ++i) { const bool vis = c == 0 ? crow(i, 0) >= thr : crow(i, 0) <= thr; p[i] = vis ? p[i] : 0.f; }
;                 }
;                 float s4 = 0.f;
; #pragma unroll
;                 for (int i = 0; i < 16; ++i) s4 += p[i];
;                 rs[cb] += s4;
; #pragma unroll
;                 for (int s = 0; s < 2; ++s) {
;                     u32x4 w; w.x = cvtpk(p[8 * s], p[8 * s + 1]); w.y = cvtpk(p[8 * s + 2], p[8 * s + 3]); w.z = cvtpk(p[8 * s + 4], p[8 * s + 5]); w.w = cvtpk(p[8 * s + 6], p[8 * s + 7]);
;                     const bf16x8_t pb = __builtin_bit_cast(bf16x8_t, w);
;                     o[0][cb] = MFMA32(vf[0][s], pb, o[0][cb]); o[1][cb] = MFMA32(vf[1][s], pb, o[1][cb]);
;                 }
	v_mfma_f32_32x32x16_bf16 v[66:81], v[146:149], v[82:85], v[66:81]
	v_mfma_f32_32x32x16_bf16 v[50:65], v[154:157], v[82:85], v[50:65]
	v_exp_f32_e32 v98, v98
	v_exp_f32_e32 v99, v99
	v_exp_f32_e32 v100, v100
	v_exp_f32_e32 v101, v101
	v_exp_f32_e32 v102, v102
	v_mfma_f32_32x32x16_bf16 v[66:81], v[150:153], v[86:89], v[66:81]
	v_exp_f32_e32 v103, v103
	v_exp_f32_e32 v104, v104
	v_exp_f32_e32 v105, v105
	v_exp_f32_e32 v106, v106
	v_exp_f32_e32 v107, v107
	v_mfma_f32_32x32x16_bf16 v[50:65], v[158:161], v[86:89], v[50:65]
	v_exp_f32_e32 v108, v108
	v_exp_f32_e32 v109, v109
	v_exp_f32_e32 v110, v110
	v_exp_f32_e32 v111, v111
	v_exp_f32_e32 v112, v112
	s_waitcnt lgkmcnt(0)
	v_mfma_f32_32x32x16_bf16 v[82:97], v[238:241], v[114:117], v[18:33]
	v_exp_f32_e32 v113, v113
	v_add_f32_e32 v182, v98, v182
	v_add_f32_e32 v182, v99, v182
	v_add_f32_e32 v182, v100, v182
	v_add_f32_e32 v182, v101, v182
	v_mfma_f32_32x32x16_bf16 v[82:97], v[242:245], v[118:121], v[82:97]
	v_add_f32_e32 v182, v102, v182
	v_add_f32_e32 v182, v103, v182
	v_add_f32_e32 v182, v104, v182
	v_add_f32_e32 v182, v105, v182
	v_add_f32_e32 v182, v106, v182
	v_mfma_f32_32x32x16_bf16 v[82:97], v[246:249], v[122:125], v[82:97]
	v_add_f32_e32 v182, v107, v182
	v_add_f32_e32 v182, v108, v182
	v_add_f32_e32 v182, v109, v182
	v_add_f32_e32 v182, v110, v182
	v_add_f32_e32 v182, v111, v182
	v_mfma_f32_32x32x16_bf16 v[82:97], v[204:207], v[126:129], v[82:97]
	v_add_f32_e32 v182, v112, v182
	v_add_f32_e32 v182, v113, v182
	v_cvt_pk_bf16_f32 v98, v98, v99
	v_cvt_pk_bf16_f32 v99, v100, v101
	v_cvt_pk_bf16_f32 v100, v102, v103
	v_cvt_pk_bf16_f32 v101, v104, v105
	v_cvt_pk_bf16_f32 v102, v106, v107
	v_cvt_pk_bf16_f32 v103, v108, v109
	v_cvt_pk_bf16_f32 v104, v110, v111
	v_cvt_pk_bf16_f32 v105, v112, v113
	s_nop 0
	s_waitcnt lgkmcnt(0)
	v_mfma_f32_32x32x16_bf16 v[34:49], v[146:149], v[98:101], v[34:49]
	v_mfma_f32_32x32x16_bf16 v[2:17], v[154:157], v[98:101], v[2:17]
	v_exp_f32_e32 v82, v82
	v_exp_f32_e32 v83, v83
	v_exp_f32_e32 v84, v84
	v_exp_f32_e32 v85, v85
	v_exp_f32_e32 v86, v86
	v_mfma_f32_32x32x16_bf16 v[34:49], v[150:153], v[102:105], v[34:49]
	v_exp_f32_e32 v87, v87
	v_exp_f32_e32 v88, v88
	v_exp_f32_e32 v89, v89
	v_exp_f32_e32 v90, v90
	v_exp_f32_e32 v91, v91
	v_mfma_f32_32x32x16_bf16 v[2:17], v[158:161], v[102:105], v[2:17]
	ds_read_b128 v[146:149], v164 offset:64
	ds_read_b128 v[150:153], v164 offset:96
	ds_read_b128 v[154:157], v165 offset:64
	ds_read_b128 v[158:161], v165 offset:96
	v_exp_f32_e32 v92, v92
	v_exp_f32_e32 v93, v93
	v_exp_f32_e32 v94, v94
	v_exp_f32_e32 v95, v95
	v_exp_f32_e32 v96, v96
	s_waitcnt lgkmcnt(0)
	v_mfma_f32_32x32x16_bf16 v[98:113], v[238:241], v[130:133], v[18:33]
	v_exp_f32_e32 v97, v97
	v_add_f32_e32 v183, v82, v183
	v_add_f32_e32 v183, v83, v183
	v_add_f32_e32 v183, v84, v183
	v_add_f32_e32 v183, v85, v183
	v_mfma_f32_32x32x16_bf16 v[98:113], v[242:245], v[134:137], v[98:113]
	v_add_f32_e32 v183, v86, v183
	v_add_f32_e32 v183, v87, v183
	v_add_f32_e32 v183, v88, v183
	v_add_f32_e32 v183, v89, v183
	v_add_f32_e32 v183, v90, v183
	v_mfma_f32_32x32x16_bf16 v[98:113], v[246:249], v[138:141], v[98:113]
	v_add_f32_e32 v183, v91, v183
	v_add_f32_e32 v183, v92, v183
	v_add_f32_e32 v183, v93, v183
	v_add_f32_e32 v183, v94, v183
	v_add_f32_e32 v183, v95, v183
	v_mfma_f32_32x32x16_bf16 v[98:113], v[204:207], v[142:145], v[98:113]
	ds_read_b128 v[238:241], v163 offset:9216
	ds_read_b128 v[242:245], v163 offset:9248
	ds_read_b128 v[246:249], v163 offset:9280
	ds_read_b128 v[204:207], v163 offset:9312
	v_add_f32_e32 v183, v96, v183
	v_add_f32_e32 v183, v97, v183
	v_cvt_pk_bf16_f32 v82, v82, v83
	v_cvt_pk_bf16_f32 v83, v84, v85
	v_cvt_pk_bf16_f32 v84, v86, v87
	v_cvt_pk_bf16_f32 v85, v88, v89
	v_cvt_pk_bf16_f32 v86, v90, v91
	v_cvt_pk_bf16_f32 v87, v92, v93
	v_cvt_pk_bf16_f32 v88, v94, v95
	v_cvt_pk_bf16_f32 v89, v96, v97
	s_nop 0
	s_waitcnt lgkmcnt(0)
	v_mfma_f32_32x32x16_bf16 v[66:81], v[146:149], v[82:85], v[66:81]
	v_mfma_f32_32x32x16_bf16 v[50:65], v[154:157], v[82:85], v[50:65]
	v_exp_f32_e32 v98, v98
	v_exp_f32_e32 v99, v99
	v_exp_f32_e32 v100, v100
	v_exp_f32_e32 v101, v101
	v_exp_f32_e32 v102, v102
	v_mfma_f32_32x32x16_bf16 v[66:81], v[150:153], v[86:89], v[66:81]
	v_exp_f32_e32 v103, v103
	v_exp_f32_e32 v104, v104
	v_exp_f32_e32 v105, v105
	v_exp_f32_e32 v106, v106
	v_exp_f32_e32 v107, v107
	v_mfma_f32_32x32x16_bf16 v[50:65], v[158:161], v[86:89], v[50:65]
	v_exp_f32_e32 v108, v108
	v_exp_f32_e32 v109, v109
	v_exp_f32_e32 v110, v110
	v_exp_f32_e32 v111, v111
	v_exp_f32_e32 v112, v112
	s_waitcnt lgkmcnt(0)
	v_mfma_f32_32x32x16_bf16 v[82:97], v[238:241], v[114:117], v[18:33]
	v_exp_f32_e32 v113, v113
	v_add_f32_e32 v182, v98, v182
	v_add_f32_e32 v182, v99, v182
	v_add_f32_e32 v182, v100, v182
	v_add_f32_e32 v182, v101, v182
	v_mfma_f32_32x32x16_bf16 v[82:97], v[242:245], v[118:121], v[82:97]
	v_add_f32_e32 v182, v102, v182
	v_add_f32_e32 v182, v103, v182
	v_add_f32_e32 v182, v104, v182
	v_add_f32_e32 v182, v105, v182
	v_add_f32_e32 v182, v106, v182
	v_mfma_f32_32x32x16_bf16 v[82:97], v[246:249], v[122:125], v[82:97]
	v_add_f32_e32 v182, v107, v182
	v_add_f32_e32 v182, v108, v182
	v_add_f32_e32 v182, v109, v182
	v_add_f32_e32 v182, v110, v182
	v_add_f32_e32 v182, v111, v182
	v_mfma_f32_32x32x16_bf16 v[82:97], v[204:207], v[126:129], v[82:97]
	v_add_f32_e32 v182, v112, v182
	v_add_f32_e32 v182, v113, v182
	v_cvt_pk_bf16_f32 v98, v98, v99
	v_cvt_pk_bf16_f32 v99, v100, v101
	v_cvt_pk_bf16_f32 v100, v102, v103
	v_cvt_pk_bf16_f32 v101, v104, v105
	v_cvt_pk_bf16_f32 v102, v106, v107
	v_cvt_pk_bf16_f32 v103, v108, v109
	v_cvt_pk_bf16_f32 v104, v110, v111
	v_cvt_pk_bf16_f32 v105, v112, v113
	s_nop 0
	s_waitcnt lgkmcnt(0)
; __device__ __forceinline__ unsigned cvtpk(float lo, float hi) { f32x2_t v = {lo, hi}; bf16x2_t b = __builtin_convertvector(v, bf16x2_t); return __builtin_bit_cast(unsigned, b); }
; #define LAS __attribute__((address_space(3)))
; __device__ __forceinline__ bool attn_unit(const Ptrs& P, LAS unsigned char* lds, int unit, int tid, int wave, int lane, bool pre, int nxt) {
;     ...
;         for (int kt = 0; kt < 4; ++kt) {
;             if (c == 0 && 32 * kt + 31 < q0) continue;
;             if (c == 2 && 32 * kt > q0 + 63) continue;
;             bf16x8_t kf[4], vf[2][2];
; #pragma unroll
;             for (int ds = 0; ds < 4; ++ds) kf[ds] = *(const LAS bf16x8_t*)(Kl + (32 * kt + r) * AT_KP + (16 * ds + 8 * hh) * 2);
; #pragma unroll
;             for (int db = 0; db < 2; ++db)
; #pragma unroll
;                 for (int s = 0; s < 2; ++s) vf[db][s] = *(const LAS bf16x8_t*)(Vl + (32 * db + r) * AT_VP + (32 * kt + 16 * s + 8 * hh) * 2);
; #pragma unroll
;             for (int cb = 0; cb < 2; ++cb) {
;                 const int dq = 32 * kt - (q0 + 32 * cb);
;                 if ((c == 0 && dq < 0) || (c == 2 && dq > 0)) continue;
;                 const bool diag = (c == 0 || c == 2) && dq == 0;
;                 f32x16 st = MFMA32(kf[0], qf[cb][0], negm);
;                 st = MFMA32(kf[1], qf[cb][1], st); st = MFMA32(kf[2], qf[cb][2], st); st = MFMA32(kf[3], qf[cb][3], st);
;                 float p[16];
; #pragma unroll
;                 for (int i = 0; i < 16; ++i) p[i] = __builtin_amdgcn_exp2f(st[i]);
;                 if (diag) {
;                     const int thr = r - 4 * hh;
; #pragma unroll
;                     for (int i = 0; i < 16; ++i) { const bool vis = c == 0 ? crow(i, 0) >= thr : crow(i, 0) <= thr; p[i] = vis ? p[i] : 0.f; }
;                 }
;                 float s4 = 0.f;
; #pragma unroll
;                 for (int i = 0; i < 16; ++i) s4 += p[i];
;                 rs[cb] += s4;
; #pragma unroll
;                 for (int s = 0; s < 2; ++s) {
;                     u32x4 w; w.x = cvtpk(p[8 * s], p[8 * s + 1]); w.y = cvtpk(p[8 * s + 2], p[8 * s + 3]); w.z = cvtpk(p[8 * s + 4], p[8 * s + 5]); w.w = cvtpk(p[8 * s + 6], p[8 * s + 7]);
;                     const bf16x8_t pb = __builtin_bit_cast(bf16x8_t, w);
;                     o[0][cb] = MFMA32(vf[0][s], pb, o[0][cb]); o[1][cb] = MFMA32(vf[1][s], pb, o[1][cb]);
;                 }
	v_mfma_f32_32x32x16_bf16 v[34:49], v[146:149], v[98:101], v[34:49]
	v_mfma_f32_32x32x16_bf16 v[2:17], v[154:157], v[98:101], v[2:17]
	v_exp_f32_e32 v82, v82
	v_exp_f32_e32 v83, v83
	v_exp_f32_e32 v84, v84
	v_exp_f32_e32 v85, v85
	v_exp_f32_e32 v86, v86
	v_mfma_f32_32x32x16_bf16 v[34:49], v[150:153], v[102:105], v[34:49]
	v_exp_f32_e32 v87, v87
	v_exp_f32_e32 v88, v88
	v_exp_f32_e32 v89, v89
	v_exp_f32_e32 v90, v90
	v_exp_f32_e32 v91, v91
	v_mfma_f32_32x32x16_bf16 v[2:17], v[158:161], v[102:105], v[2:17]
	ds_read_b128 v[146:149], v164 offset:128
	ds_read_b128 v[150:153], v164 offset:160
	ds_read_b128 v[154:157], v165 offset:128
	ds_read_b128 v[158:161], v165 offset:160
	v_exp_f32_e32 v92, v92
	v_exp_f32_e32 v93, v93
	v_exp_f32_e32 v94, v94
	v_exp_f32_e32 v95, v95
	v_exp_f32_e32 v96, v96
	s_waitcnt lgkmcnt(0)
	v_mfma_f32_32x32x16_bf16 v[98:113], v[238:241], v[130:133], v[18:33]
	v_exp_f32_e32 v97, v97
	v_cmp_le_i32_e32 vcc, 0, v162
	v_cmp_le_i32_e64 s[98:99], 1, v162
	s_nop 0
	v_cndmask_b32_e32 v82, 0, v82, vcc
	v_mfma_f32_32x32x16_bf16 v[98:113], v[242:245], v[134:137], v[98:113]
	v_cmp_le_i32_e32 vcc, 2, v162
	v_cndmask_b32_e64 v83, 0, v83, s[98:99]
	v_cmp_le_i32_e64 s[98:99], 3, v162
	v_cndmask_b32_e32 v84, 0, v84, vcc
	v_cmp_le_i32_e32 vcc, 8, v162
	v_mfma_f32_32x32x16_bf16 v[98:113], v[246:249], v[138:141], v[98:113]
	v_cndmask_b32_e64 v85, 0, v85, s[98:99]
	v_cmp_le_i32_e64 s[98:99], 9, v162
	v_cndmask_b32_e32 v86, 0, v86, vcc
	v_cmp_le_i32_e32 vcc, 10, v162
	v_cndmask_b32_e64 v87, 0, v87, s[98:99]
	v_mfma_f32_32x32x16_bf16 v[98:113], v[204:207], v[142:145], v[98:113]
	ds_read_b128 v[238:241], v163 offset:13824
	ds_read_b128 v[242:245], v163 offset:13856
	ds_read_b128 v[246:249], v163 offset:13888
	ds_read_b128 v[204:207], v163 offset:13920
	v_cmp_le_i32_e64 s[98:99], 11, v162
	v_cndmask_b32_e32 v88, 0, v88, vcc
	v_cmp_le_i32_e32 vcc, 16, v162
	v_cndmask_b32_e64 v89, 0, v89, s[98:99]
	v_cmp_le_i32_e64 s[98:99], 17, v162
	v_cndmask_b32_e32 v90, 0, v90, vcc
	v_cmp_le_i32_e32 vcc, 18, v162
	v_cndmask_b32_e64 v91, 0, v91, s[98:99]
	v_cmp_le_i32_e64 s[98:99], 19, v162
	v_cndmask_b32_e32 v92, 0, v92, vcc
	v_cmp_le_i32_e32 vcc, 24, v162
	v_cndmask_b32_e64 v93, 0, v93, s[98:99]
	v_cmp_le_i32_e64 s[98:99], 25, v162
	v_cndmask_b32_e32 v94, 0, v94, vcc
	v_cmp_le_i32_e32 vcc, 26, v162
	v_cndmask_b32_e64 v95, 0, v95, s[98:99]
	v_cmp_le_i32_e64 s[98:99], 27, v162
	v_cndmask_b32_e32 v96, 0, v96, vcc
	s_nop 0
	v_cndmask_b32_e64 v97, 0, v97, s[98:99]
	s_nop 0
	v_add_f32_e32 v183, v82, v183
	v_add_f32_e32 v183, v83, v183
	v_add_f32_e32 v183, v84, v183
	v_add_f32_e32 v183, v85, v183
	v_add_f32_e32 v183, v86, v183
	v_add_f32_e32 v183, v87, v183
	v_add_f32_e32 v183, v88, v183
	v_add_f32_e32 v183, v89, v183
	v_add_f32_e32 v183, v90, v183
	v_add_f32_e32 v183, v91, v183
	v_add_f32_e32 v183, v92, v183
	v_add_f32_e32 v183, v93, v183
	v_add_f32_e32 v183, v94, v183
	v_add_f32_e32 v183, v95, v183
	v_add_f32_e32 v183, v96, v183
	v_add_f32_e32 v183, v97, v183
	v_cvt_pk_bf16_f32 v82, v82, v83
	v_cvt_pk_bf16_f32 v83, v84, v85
	v_cvt_pk_bf16_f32 v84, v86, v87
	v_cvt_pk_bf16_f32 v85, v88, v89
	v_cvt_pk_bf16_f32 v86, v90, v91
	v_cvt_pk_bf16_f32 v87, v92, v93
	v_cvt_pk_bf16_f32 v88, v94, v95
	v_cvt_pk_bf16_f32 v89, v96, v97
	s_nop 0
	s_waitcnt lgkmcnt(0)
	v_mfma_f32_32x32x16_bf16 v[66:81], v[146:149], v[82:85], v[66:81]
	v_mfma_f32_32x32x16_bf16 v[50:65], v[154:157], v[82:85], v[50:65]
	v_exp_f32_e32 v98, v98
	v_exp_f32_e32 v99, v99
	v_exp_f32_e32 v100, v100
	v_exp_f32_e32 v101, v101
	v_exp_f32_e32 v102, v102
	v_mfma_f32_32x32x16_bf16 v[66:81], v[150:153], v[86:89], v[66:81]
	v_exp_f32_e32 v103, v103
	v_exp_f32_e32 v104, v104
	v_exp_f32_e32 v105, v105
	v_exp_f32_e32 v106, v106
	v_exp_f32_e32 v107, v107
	v_mfma_f32_32x32x16_bf16 v[50:65], v[158:161], v[86:89], v[50:65]
	v_exp_f32_e32 v108, v108
	v_exp_f32_e32 v109, v109
	v_exp_f32_e32 v110, v110
	v_exp_f32_e32 v111, v111
	v_exp_f32_e32 v112, v112
	s_waitcnt lgkmcnt(0)
; __device__ __forceinline__ unsigned cvtpk(float lo, float hi) { f32x2_t v = {lo, hi}; bf16x2_t b = __builtin_convertvector(v, bf16x2_t); return __builtin_bit_cast(unsigned, b); }
; #define LAS __attribute__((address_space(3)))
; __device__ __forceinline__ bool attn_unit(const Ptrs& P, LAS unsigned char* lds, int unit, int tid, int wave, int lane, bool pre, int nxt) {
;     ...
;         for (int kt = 0; kt < 4; ++kt) {
;             if (c == 0 && 32 * kt + 31 < q0) continue;
;             if (c == 2 && 32 * kt > q0 + 63) continue;
;             bf16x8_t kf[4], vf[2][2];
; #pragma unroll
;             for (int ds = 0; ds < 4; ++ds) kf[ds] = *(const LAS bf16x8_t*)(Kl + (32 * kt + r) * AT_KP + (16 * ds + 8 * hh) * 2);
; #pragma unroll
;             for (int db = 0; db < 2; ++db)
; #pragma unroll
;                 for (int s = 0; s < 2; ++s) vf[db][s] = *(const LAS bf16x8_t*)(Vl + (32 * db + r) * AT_VP + (32 * kt + 16 * s + 8 * hh) * 2);
; #pragma unroll
;             for (int cb = 0; cb < 2; ++cb) {
;                 const int dq = 32 * kt - (q0 + 32 * cb);
;                 if ((c == 0 && dq < 0) || (c == 2 && dq > 0)) continue;
;                 const bool diag = (c == 0 || c == 2) && dq == 0;
;                 f32x16 st = MFMA32(kf[0], qf[cb][0], negm);
;                 st = MFMA32(kf[1], qf[cb][1], st); st = MFMA32(kf[2], qf[cb][2], st); st = MFMA32(kf[3], qf[cb][3], st);
;                 float p[16];
; #pragma unroll
;                 for (int i = 0; i < 16; ++i) p[i] = __builtin_amdgcn_exp2f(st[i]);
;                 if (diag) {
;                     const int thr = r - 4 * hh;
; #pragma unroll
;                     for (int i = 0; i < 16; ++i) { const bool vis = c == 0 ? crow(i, 0) >= thr : crow(i, 0) <= thr; p[i] = vis ? p[i] : 0.f; }
;                 }
;                 float s4 = 0.f;
; #pragma unroll
;                 for (int i = 0; i < 16; ++i) s4 += p[i];
;                 rs[cb] += s4;
; #pragma unroll
;                 for (int s = 0; s < 2; ++s) {
;                     u32x4 w; w.x = cvtpk(p[8 * s], p[8 * s + 1]); w.y = cvtpk(p[8 * s + 2], p[8 * s + 3]); w.z = cvtpk(p[8 * s + 4], p[8 * s + 5]); w.w = cvtpk(p[8 * s + 6], p[8 * s + 7]);
;                     const bf16x8_t pb = __builtin_bit_cast(bf16x8_t, w);
;                     o[0][cb] = MFMA32(vf[0][s], pb, o[0][cb]); o[1][cb] = MFMA32(vf[1][s], pb, o[1][cb]);
;                 }
	v_mfma_f32_32x32x16_bf16 v[82:97], v[238:241], v[130:133], v[18:33]
	v_exp_f32_e32 v113, v113
	v_add_f32_e32 v182, v98, v182
	v_add_f32_e32 v182, v99, v182
	v_add_f32_e32 v182, v100, v182
	v_add_f32_e32 v182, v101, v182
	v_mfma_f32_32x32x16_bf16 v[82:97], v[242:245], v[134:137], v[82:97]
	v_add_f32_e32 v182, v102, v182
	v_add_f32_e32 v182, v103, v182
	v_add_f32_e32 v182, v104, v182
	v_add_f32_e32 v182, v105, v182
	v_add_f32_e32 v182, v106, v182
	v_mfma_f32_32x32x16_bf16 v[82:97], v[246:249], v[138:141], v[82:97]
	v_add_f32_e32 v182, v107, v182
	v_add_f32_e32 v182, v108, v182
	v_add_f32_e32 v182, v109, v182
	v_add_f32_e32 v182, v110, v182
	v_add_f32_e32 v182, v111, v182
	v_mfma_f32_32x32x16_bf16 v[82:97], v[204:207], v[142:145], v[82:97]
	v_add_f32_e32 v182, v112, v182
	v_add_f32_e32 v182, v113, v182
	v_cvt_pk_bf16_f32 v98, v98, v99
	v_cvt_pk_bf16_f32 v99, v100, v101
	v_cvt_pk_bf16_f32 v100, v102, v103
	v_cvt_pk_bf16_f32 v101, v104, v105
	v_cvt_pk_bf16_f32 v102, v106, v107
	v_cvt_pk_bf16_f32 v103, v108, v109
	v_cvt_pk_bf16_f32 v104, v110, v111
	v_cvt_pk_bf16_f32 v105, v112, v113
	s_nop 0
	s_waitcnt lgkmcnt(0)
	v_mfma_f32_32x32x16_bf16 v[34:49], v[146:149], v[98:101], v[34:49]
	v_mfma_f32_32x32x16_bf16 v[2:17], v[154:157], v[98:101], v[2:17]
	v_exp_f32_e32 v82, v82
	v_exp_f32_e32 v83, v83
	v_exp_f32_e32 v84, v84
	v_exp_f32_e32 v85, v85
	v_exp_f32_e32 v86, v86
	v_mfma_f32_32x32x16_bf16 v[34:49], v[150:153], v[102:105], v[34:49]
	v_exp_f32_e32 v87, v87
	v_exp_f32_e32 v88, v88
	v_exp_f32_e32 v89, v89
	v_exp_f32_e32 v90, v90
	v_exp_f32_e32 v91, v91
	v_mfma_f32_32x32x16_bf16 v[2:17], v[158:161], v[102:105], v[2:17]
	ds_read_b128 v[146:149], v164 offset:192
	ds_read_b128 v[150:153], v164 offset:224
	ds_read_b128 v[154:157], v165 offset:192
	ds_read_b128 v[158:161], v165 offset:224
	v_exp_f32_e32 v92, v92
	v_exp_f32_e32 v93, v93
	v_exp_f32_e32 v94, v94
	v_exp_f32_e32 v95, v95
	v_exp_f32_e32 v96, v96
	v_exp_f32_e32 v97, v97
	v_cmp_le_i32_e32 vcc, 0, v162
	v_cmp_le_i32_e64 s[98:99], 1, v162
	s_nop 0
	v_cndmask_b32_e32 v82, 0, v82, vcc
	v_cmp_le_i32_e32 vcc, 2, v162
	v_cndmask_b32_e64 v83, 0, v83, s[98:99]
	v_cmp_le_i32_e64 s[98:99], 3, v162
	v_cndmask_b32_e32 v84, 0, v84, vcc
	v_cmp_le_i32_e32 vcc, 8, v162
	v_cndmask_b32_e64 v85, 0, v85, s[98:99]
	v_cmp_le_i32_e64 s[98:99], 9, v162
	v_cndmask_b32_e32 v86, 0, v86, vcc
	v_cmp_le_i32_e32 vcc, 10, v162
	v_cndmask_b32_e64 v87, 0, v87, s[98:99]
	v_cmp_le_i32_e64 s[98:99], 11, v162
	v_cndmask_b32_e32 v88, 0, v88, vcc
	v_cmp_le_i32_e32 vcc, 16, v162
	v_cndmask_b32_e64 v89, 0, v89, s[98:99]
	v_cmp_le_i32_e64 s[98:99], 17, v162
	v_cndmask_b32_e32 v90, 0, v90, vcc
	v_cmp_le_i32_e32 vcc, 18, v162
	v_cndmask_b32_e64 v91, 0, v91, s[98:99]
	v_cmp_le_i32_e64 s[98:99], 19, v162
	v_cndmask_b32_e32 v92, 0, v92, vcc
	v_cmp_le_i32_e32 vcc, 24, v162
	v_cndmask_b32_e64 v93, 0, v93, s[98:99]
	v_cmp_le_i32_e64 s[98:99], 25, v162
	v_cndmask_b32_e32 v94, 0, v94, vcc
	v_cmp_le_i32_e32 vcc, 26, v162
	v_cndmask_b32_e64 v95, 0, v95, s[98:99]
	v_cmp_le_i32_e64 s[98:99], 27, v162
	v_cndmask_b32_e32 v96, 0, v96, vcc
	s_nop 0
	v_cndmask_b32_e64 v97, 0, v97, s[98:99]
	s_nop 0
	v_add_f32_e32 v182, v82, v182
	v_add_f32_e32 v182, v83, v182
	v_add_f32_e32 v182, v84, v182
	v_add_f32_e32 v182, v85, v182
	v_add_f32_e32 v182, v86, v182
	v_add_f32_e32 v182, v87, v182
	v_add_f32_e32 v182, v88, v182
	v_add_f32_e32 v182, v89, v182
	v_add_f32_e32 v182, v90, v182
	v_add_f32_e32 v182, v91, v182
	v_add_f32_e32 v182, v92, v182
	v_add_f32_e32 v182, v93, v182
	v_add_f32_e32 v182, v94, v182
	v_add_f32_e32 v182, v95, v182
	v_add_f32_e32 v182, v96, v182
	v_add_f32_e32 v182, v97, v182
	v_cvt_pk_bf16_f32 v82, v82, v83
	v_cvt_pk_bf16_f32 v83, v84, v85
	v_cvt_pk_bf16_f32 v84, v86, v87
	v_cvt_pk_bf16_f32 v85, v88, v89
	v_cvt_pk_bf16_f32 v86, v90, v91
	v_cvt_pk_bf16_f32 v87, v92, v93
	v_cvt_pk_bf16_f32 v88, v94, v95
	v_cvt_pk_bf16_f32 v89, v96, v97
	s_nop 1
	s_waitcnt lgkmcnt(0)
	v_mfma_f32_32x32x16_bf16 v[34:49], v[146:149], v[82:85], v[34:49]
	v_mfma_f32_32x32x16_bf16 v[2:17], v[154:157], v[82:85], v[2:17]
	v_mfma_f32_32x32x16_bf16 v[34:49], v[150:153], v[86:89], v[34:49]
	v_mfma_f32_32x32x16_bf16 v[2:17], v[158:161], v[86:89], v[2:17]
